# GEMM K-loops: LDS-DMA addresses in saddr form (scalar base + 32-bit lane offset) instead of 64-bit VALU adds; plus previous attention edits
# speedup vs baseline: 1.0002x; 1.0002x over previous
; #define PG8_STAGE(bufoff, gbase, voff) do { _Pragma("unroll") for (int _i = 0; _i < 2; ++_i) \
;         __builtin_amdgcn_global_load_lds((const unsigned*)((const char*)(gbase) + (voff)[_i]), (PG8_LAS unsigned*)(lds + (bufoff) + ldsw + _i * 8192), 16, 0, 0); } while (0)
; #define PG8_LDA(dst, b, h) do { _Pragma("unroll") for (int m = 0; m < 4; ++m) _Pragma("unroll") for (int k = 0; k < 2; ++k) dst[m][k] = *(const PG8_LAS bf16x8*)(lds + PG8_SA(b, h) + aoff + m * 2048 + k * 1024); } while (0)
; #define PG8_LDB(dst, b, h) do { _Pragma("unroll") for (int n = 0; n < 2; ++n) _Pragma("unroll") for (int k = 0; k < 2; ++k) dst[n][k] = *(const PG8_LAS bf16x8*)(lds + PG8_SB(b, h) + boff + n * 2048 + k * 1024); } while (0)
; #define PG8_MMA(ai, bj, At, Bt) do { __builtin_amdgcn_s_setprio(1); _Pragma("unroll") for (int m = 0; m < 4; ++m) _Pragma("unroll") for (int n = 0; n < 2; ++n) _Pragma("unroll") for (int k = 0; k < 2; ++k) \
;         acc[ai][bj][m][n] = __builtin_amdgcn_mfma_f32_16x16x32_bf16(Bt[n][k], At[m][k], acc[ai][bj][m][n], 0, 0, 0); __builtin_amdgcn_s_setprio(0); } while (0)
; #define PG8_WAIT_V(n) asm volatile("s_waitcnt vmcnt(" #n ")" ::: "memory")
; #define PG8_BAR __builtin_amdgcn_s_barrier()
; template <class Epi, class Sched, bool ALIGN_EPI = false, bool SP2 = false>
; __device__ __forceinline__ void gemm_phase(PG8_LAS unsigned char* lds, const Gemm g, const Sched& S, const Epi& E) {
;     ...
;         for (int t = 0; t < nt; t += 2) {
;             const bool last = (t == nt - 2);
;             const char* a1 = cA + (size_t)(t + 1) * kstep;
;             const char* a2 = last ? nA : cA + (size_t)(t + 2) * kstep; const char* b2 = last ? nB : cB + (size_t)(t + 2) * kstep;
;             const char* a3 = a2 + kstep; const char* b3 = b2 + kstep;
;             if (last && has_next) S.a_ready(nxt);
;             if constexpr (SP2) {
;             PG8_LDB(B0, 0, 0); PG8_LDB(B1, 0, 1); PG8_SCHED; PG8_LDA(At, 0, 0); PG8_STAGE(PG8_SA(1, 1), a1 + hstep, voffA);
;             PG8_WAIT_V(8); PG8_WAIT_L(0); PG8_BAR; PG8_MMA(0, 0, At, B0); PG8_MMA(0, 1, At, B1); PG8_BAR; PG8_SCHED;
;             PG8_LDA(At, 0, 1); PG8_STAGE(PG8_SB(0, 0), b2, voffB); PG8_STAGE(PG8_SB(0, 1), b2 + hstep, voffB); PG8_STAGE(PG8_SA(0, 0), a2, voffA);
;             PG8_WAIT_V(8); PG8_WAIT_L(0); PG8_BAR; PG8_MMA(1, 0, At, B0); PG8_MMA(1, 1, At, B1); PG8_BAR; PG8_SCHED;
.LBB0_164:
	s_add_u32 s58, s72, 0xfffc0080
	s_addc_u32 s59, s73, -1
	s_add_i32 s84, 0, 0x10000
	s_cmp_eq_u32 s94, 12
	s_cselect_b32 s65, s36, s59
	s_cselect_b32 s64, s37, s58
	v_add_u32_e32 v140, s84, v146
	s_cselect_b32 s59, s51, s93
	s_cselect_b32 s58, s53, s92
	s_add_i32 s96, 0, 0x14000
	ds_read_b128 v[142:145], v140
	ds_read_b128 v[150:153], v140 offset:1024
	ds_read_b128 v[154:157], v140 offset:2048
	ds_read_b128 v[158:161], v140 offset:3072
	v_add_u32_e32 v140, s96, v146
	ds_read_b128 v[162:165], v140
	ds_read_b128 v[166:169], v140 offset:1024
	ds_read_b128 v[170:173], v140 offset:2048
	ds_read_b128 v[174:177], v140 offset:3072
	s_add_i32 m0, s19, 0xc000
	ds_read_b128 v[178:181], v148
	ds_read_b128 v[182:185], v148 offset:1024
	ds_read_b128 v[190:193], v148 offset:2048
	ds_read_b128 v[194:197], v148 offset:3072
	ds_read_b128 v[198:201], v148 offset:4096
	ds_read_b128 v[202:205], v148 offset:5120
	ds_read_b128 v[206:209], v148 offset:6144
	ds_read_b128 v[228:231], v148 offset:7168
	global_load_lds_dwordx4 v136, s[72:73]
	s_add_i32 m0, s19, 0xe000
	s_nop 0
	global_load_lds_dwordx4 v138, s[72:73]
	s_waitcnt vmcnt(8)
	s_waitcnt lgkmcnt(0)
	s_barrier
	s_setprio 1
	s_waitcnt lgkmcnt(0)
	v_mfma_f32_16x16x32_bf16 v[124:127], v[142:145], v[178:181], v[124:127]
	v_mfma_f32_16x16x32_bf16 v[120:123], v[154:157], v[178:181], v[120:123]
	v_mfma_f32_16x16x32_bf16 v[116:119], v[142:145], v[190:193], v[116:119]
	v_mfma_f32_16x16x32_bf16 v[112:115], v[154:157], v[190:193], v[112:115]
	v_mfma_f32_16x16x32_bf16 v[108:111], v[142:145], v[198:201], v[108:111]
	v_mfma_f32_16x16x32_bf16 v[104:107], v[154:157], v[198:201], v[104:107]
	v_mfma_f32_16x16x32_bf16 v[100:103], v[142:145], v[206:209], v[100:103]
	v_mfma_f32_16x16x32_bf16 v[96:99], v[154:157], v[206:209], v[96:99]
	v_mfma_f32_16x16x32_bf16 v[124:127], v[150:153], v[182:185], v[124:127]
	v_mfma_f32_16x16x32_bf16 v[120:123], v[158:161], v[182:185], v[120:123]
	v_mfma_f32_16x16x32_bf16 v[116:119], v[150:153], v[194:197], v[116:119]
	v_mfma_f32_16x16x32_bf16 v[112:115], v[158:161], v[194:197], v[112:115]
	v_mfma_f32_16x16x32_bf16 v[108:111], v[150:153], v[202:205], v[108:111]
	v_mfma_f32_16x16x32_bf16 v[104:107], v[158:161], v[202:205], v[104:107]
	v_mfma_f32_16x16x32_bf16 v[100:103], v[150:153], v[228:231], v[100:103]
	v_mfma_f32_16x16x32_bf16 v[96:99], v[158:161], v[228:231], v[96:99]
	s_setprio 0
	s_setprio 1
	v_mfma_f32_16x16x32_bf16 v[92:95], v[162:165], v[178:181], v[92:95]
	v_mfma_f32_16x16x32_bf16 v[88:91], v[170:173], v[178:181], v[88:91]
	v_mfma_f32_16x16x32_bf16 v[84:87], v[162:165], v[190:193], v[84:87]
	v_mfma_f32_16x16x32_bf16 v[80:83], v[170:173], v[190:193], v[80:83]
	v_mfma_f32_16x16x32_bf16 v[76:79], v[162:165], v[198:201], v[76:79]
	v_mfma_f32_16x16x32_bf16 v[72:75], v[170:173], v[198:201], v[72:75]
	v_mfma_f32_16x16x32_bf16 v[68:71], v[162:165], v[206:209], v[68:71]
	v_mfma_f32_16x16x32_bf16 v[64:67], v[170:173], v[206:209], v[64:67]
	v_mfma_f32_16x16x32_bf16 v[92:95], v[166:169], v[182:185], v[92:95]
	v_mfma_f32_16x16x32_bf16 v[88:91], v[174:177], v[182:185], v[88:91]
	v_mfma_f32_16x16x32_bf16 v[84:87], v[166:169], v[194:197], v[84:87]
	v_mfma_f32_16x16x32_bf16 v[80:83], v[174:177], v[194:197], v[80:83]
	v_mfma_f32_16x16x32_bf16 v[76:79], v[166:169], v[202:205], v[76:79]
	v_mfma_f32_16x16x32_bf16 v[72:75], v[174:177], v[202:205], v[72:75]
	v_mfma_f32_16x16x32_bf16 v[68:71], v[166:169], v[228:231], v[68:71]
	v_mfma_f32_16x16x32_bf16 v[64:67], v[174:177], v[228:231], v[64:67]
	s_setprio 0
	s_barrier
	s_add_i32 s84, s84, s18
	s_mov_b32 m0, s84
	ds_read_b128 v[178:181], v148 offset:16384
	ds_read_b128 v[182:185], v148 offset:17408
	ds_read_b128 v[190:193], v148 offset:18432
	ds_read_b128 v[194:197], v148 offset:19456
	ds_read_b128 v[198:201], v148 offset:20480
	ds_read_b128 v[202:205], v148 offset:21504
	ds_read_b128 v[206:209], v148 offset:22528
	ds_read_b128 v[228:231], v148 offset:23552
	global_load_lds_dwordx4 v128, s[58:59]
	s_add_i32 m0, s84, 0x2000
	s_add_u32 s84, s58, 0x40000
	s_addc_u32 s85, s59, 0
	s_add_i32 s96, s96, s18
	global_load_lds_dwordx4 v130, s[58:59]
	s_mov_b32 m0, s96
	s_nop 0
	global_load_lds_dwordx4 v128, s[84:85]
	s_add_i32 m0, s96, 0x2000
	s_nop 0
	global_load_lds_dwordx4 v130, s[84:85]
	s_mov_b32 m0, s19
	s_nop 0
	global_load_lds_dwordx4 v134, s[64:65]
	s_mov_b32 m0, s20
	s_nop 0
	global_load_lds_dwordx4 v132, s[64:65]
	s_add_u32 s100, s64, 0x80
	s_addc_u32 s101, s65, 0
	s_waitcnt vmcnt(8)
	s_waitcnt lgkmcnt(0)
	s_barrier
	s_setprio 1
	s_waitcnt lgkmcnt(0)
	v_mfma_f32_16x16x32_bf16 v[60:63], v[142:145], v[178:181], v[60:63]
	v_mfma_f32_16x16x32_bf16 v[56:59], v[154:157], v[178:181], v[56:59]
	v_mfma_f32_16x16x32_bf16 v[52:55], v[142:145], v[190:193], v[52:55]
	v_mfma_f32_16x16x32_bf16 v[48:51], v[154:157], v[190:193], v[48:51]
	v_mfma_f32_16x16x32_bf16 v[44:47], v[142:145], v[198:201], v[44:47]
	v_mfma_f32_16x16x32_bf16 v[40:43], v[154:157], v[198:201], v[40:43]
	v_mfma_f32_16x16x32_bf16 v[36:39], v[142:145], v[206:209], v[36:39]
	v_mfma_f32_16x16x32_bf16 v[32:35], v[154:157], v[206:209], v[32:35]
	v_mfma_f32_16x16x32_bf16 v[60:63], v[150:153], v[182:185], v[60:63]
	v_mfma_f32_16x16x32_bf16 v[56:59], v[158:161], v[182:185], v[56:59]
	v_mfma_f32_16x16x32_bf16 v[52:55], v[150:153], v[194:197], v[52:55]
	v_mfma_f32_16x16x32_bf16 v[48:51], v[158:161], v[194:197], v[48:51]
	v_mfma_f32_16x16x32_bf16 v[44:47], v[150:153], v[202:205], v[44:47]
	v_mfma_f32_16x16x32_bf16 v[40:43], v[158:161], v[202:205], v[40:43]
	v_mfma_f32_16x16x32_bf16 v[36:39], v[150:153], v[228:231], v[36:39]
	v_mfma_f32_16x16x32_bf16 v[32:35], v[158:161], v[228:231], v[32:35]
	s_setprio 0
	s_setprio 1
	v_mfma_f32_16x16x32_bf16 v[28:31], v[162:165], v[178:181], v[28:31]
	v_mfma_f32_16x16x32_bf16 v[24:27], v[170:173], v[178:181], v[24:27]
	v_mfma_f32_16x16x32_bf16 v[20:23], v[162:165], v[190:193], v[20:23]
	v_mfma_f32_16x16x32_bf16 v[16:19], v[170:173], v[190:193], v[16:19]
	v_mfma_f32_16x16x32_bf16 v[12:15], v[162:165], v[198:201], v[12:15]
	v_mfma_f32_16x16x32_bf16 v[8:11], v[170:173], v[198:201], v[8:11]
	v_mfma_f32_16x16x32_bf16 v[4:7], v[162:165], v[206:209], v[4:7]
	v_mfma_f32_16x16x32_bf16 v[0:3], v[170:173], v[206:209], v[0:3]
	v_mfma_f32_16x16x32_bf16 v[28:31], v[166:169], v[182:185], v[28:31]
	v_mfma_f32_16x16x32_bf16 v[24:27], v[174:177], v[182:185], v[24:27]
	v_mfma_f32_16x16x32_bf16 v[20:23], v[166:169], v[194:197], v[20:23]
	v_mfma_f32_16x16x32_bf16 v[16:19], v[174:177], v[194:197], v[16:19]
	v_mfma_f32_16x16x32_bf16 v[12:15], v[166:169], v[202:205], v[12:15]
	v_mfma_f32_16x16x32_bf16 v[8:11], v[174:177], v[202:205], v[8:11]
	v_mfma_f32_16x16x32_bf16 v[4:7], v[166:169], v[228:231], v[4:7]
	v_mfma_f32_16x16x32_bf16 v[0:3], v[174:177], v[228:231], v[0:3]
	s_setprio 0
	s_barrier
; #define PG8_STAGE(bufoff, gbase, voff) do { _Pragma("unroll") for (int _i = 0; _i < 2; ++_i) \
;         __builtin_amdgcn_global_load_lds((const unsigned*)((const char*)(gbase) + (voff)[_i]), (PG8_LAS unsigned*)(lds + (bufoff) + ldsw + _i * 8192), 16, 0, 0); } while (0)
; #define PG8_LDA(dst, b, h) do { _Pragma("unroll") for (int m = 0; m < 4; ++m) _Pragma("unroll") for (int k = 0; k < 2; ++k) dst[m][k] = *(const PG8_LAS bf16x8*)(lds + PG8_SA(b, h) + aoff + m * 2048 + k * 1024); } while (0)
; #define PG8_LDB(dst, b, h) do { _Pragma("unroll") for (int n = 0; n < 2; ++n) _Pragma("unroll") for (int k = 0; k < 2; ++k) dst[n][k] = *(const PG8_LAS bf16x8*)(lds + PG8_SB(b, h) + boff + n * 2048 + k * 1024); } while (0)
; #define PG8_MMA(ai, bj, At, Bt) do { __builtin_amdgcn_s_setprio(1); _Pragma("unroll") for (int m = 0; m < 4; ++m) _Pragma("unroll") for (int n = 0; n < 2; ++n) _Pragma("unroll") for (int k = 0; k < 2; ++k) \
;         acc[ai][bj][m][n] = __builtin_amdgcn_mfma_f32_16x16x32_bf16(Bt[n][k], At[m][k], acc[ai][bj][m][n], 0, 0, 0); __builtin_amdgcn_s_setprio(0); } while (0)
; #define PG8_WAIT_V(n) asm volatile("s_waitcnt vmcnt(" #n ")" ::: "memory")
; #define PG8_WAIT_L(n) asm volatile("s_waitcnt lgkmcnt(" #n ")" ::: "memory")
; #define PG8_BAR __builtin_amdgcn_s_barrier()
; #define PG8_SCHED __builtin_amdgcn_sched_barrier(0)
; template <class Epi, class Sched, bool ALIGN_EPI = false, bool SP2 = false>
; __device__ __forceinline__ void gemm_phase(PG8_LAS unsigned char* lds, const Gemm g, const Sched& S, const Epi& E) {
;     ...
;             PG8_LDB(B0, 1, 0); PG8_LDB(B1, 1, 1); PG8_SCHED; PG8_LDA(At, 1, 0); PG8_STAGE(PG8_SA(0, 1), a2 + hstep, voffA);
;             PG8_WAIT_V(8); PG8_WAIT_L(0); PG8_BAR; PG8_MMA(0, 0, At, B0); PG8_MMA(0, 1, At, B1); PG8_BAR; PG8_SCHED;
;             PG8_LDA(At, 1, 1); PG8_STAGE(PG8_SB(1, 0), b3, voffB); PG8_STAGE(PG8_SB(1, 1), b3 + hstep, voffB); PG8_STAGE(PG8_SA(1, 0), a3, voffA);
;             PG8_WAIT_V(8); PG8_WAIT_L(0); PG8_BAR; PG8_MMA(1, 0, At, B0); PG8_MMA(1, 1, At, B1); PG8_BAR; PG8_SCHED;
	s_add_i32 s84, 0, 0x18000
	v_add_u32_e32 v140, s84, v146
	s_add_i32 s85, 0, 0x1c000
	ds_read_b128 v[142:145], v140
	ds_read_b128 v[150:153], v140 offset:1024
	ds_read_b128 v[154:157], v140 offset:2048
	ds_read_b128 v[158:161], v140 offset:3072
	v_add_u32_e32 v140, s85, v146
	ds_read_b128 v[162:165], v140
	ds_read_b128 v[166:169], v140 offset:1024
	ds_read_b128 v[170:173], v140 offset:2048
	ds_read_b128 v[174:177], v140 offset:3072
	s_add_u32 s64, s64, 0x40000
	s_addc_u32 s65, s65, 0
	s_mov_b32 m0, s21
	ds_read_b128 v[178:181], v148 offset:32768
	ds_read_b128 v[182:185], v148 offset:33792
	ds_read_b128 v[190:193], v148 offset:34816
	ds_read_b128 v[194:197], v148 offset:35840
	ds_read_b128 v[198:201], v148 offset:36864
	ds_read_b128 v[202:205], v148 offset:37888
	ds_read_b128 v[206:209], v148 offset:38912
	ds_read_b128 v[228:231], v148 offset:39936
	global_load_lds_dwordx4 v134, s[64:65]
	s_mov_b32 m0, s22
	s_nop 0
	global_load_lds_dwordx4 v132, s[64:65]
	s_waitcnt vmcnt(8)
	s_waitcnt lgkmcnt(0)
	s_barrier
	s_setprio 1
	s_waitcnt lgkmcnt(0)
	v_mfma_f32_16x16x32_bf16 v[124:127], v[142:145], v[178:181], v[124:127]
	v_mfma_f32_16x16x32_bf16 v[120:123], v[154:157], v[178:181], v[120:123]
	v_mfma_f32_16x16x32_bf16 v[116:119], v[142:145], v[190:193], v[116:119]
	v_mfma_f32_16x16x32_bf16 v[112:115], v[154:157], v[190:193], v[112:115]
	v_mfma_f32_16x16x32_bf16 v[108:111], v[142:145], v[198:201], v[108:111]
	v_mfma_f32_16x16x32_bf16 v[104:107], v[154:157], v[198:201], v[104:107]
	v_mfma_f32_16x16x32_bf16 v[100:103], v[142:145], v[206:209], v[100:103]
	v_mfma_f32_16x16x32_bf16 v[96:99], v[154:157], v[206:209], v[96:99]
	v_mfma_f32_16x16x32_bf16 v[124:127], v[150:153], v[182:185], v[124:127]
	v_mfma_f32_16x16x32_bf16 v[120:123], v[158:161], v[182:185], v[120:123]
	v_mfma_f32_16x16x32_bf16 v[116:119], v[150:153], v[194:197], v[116:119]
	v_mfma_f32_16x16x32_bf16 v[112:115], v[158:161], v[194:197], v[112:115]
	v_mfma_f32_16x16x32_bf16 v[108:111], v[150:153], v[202:205], v[108:111]
	v_mfma_f32_16x16x32_bf16 v[104:107], v[158:161], v[202:205], v[104:107]
	v_mfma_f32_16x16x32_bf16 v[100:103], v[150:153], v[228:231], v[100:103]
	v_mfma_f32_16x16x32_bf16 v[96:99], v[158:161], v[228:231], v[96:99]
	s_setprio 0
	s_setprio 1
	v_mfma_f32_16x16x32_bf16 v[92:95], v[162:165], v[178:181], v[92:95]
	v_mfma_f32_16x16x32_bf16 v[88:91], v[170:173], v[178:181], v[88:91]
	v_mfma_f32_16x16x32_bf16 v[84:87], v[162:165], v[190:193], v[84:87]
	v_mfma_f32_16x16x32_bf16 v[80:83], v[170:173], v[190:193], v[80:83]
	v_mfma_f32_16x16x32_bf16 v[76:79], v[162:165], v[198:201], v[76:79]
	v_mfma_f32_16x16x32_bf16 v[72:75], v[170:173], v[198:201], v[72:75]
	v_mfma_f32_16x16x32_bf16 v[68:71], v[162:165], v[206:209], v[68:71]
	v_mfma_f32_16x16x32_bf16 v[64:67], v[170:173], v[206:209], v[64:67]
	v_mfma_f32_16x16x32_bf16 v[92:95], v[166:169], v[182:185], v[92:95]
	v_mfma_f32_16x16x32_bf16 v[88:91], v[174:177], v[182:185], v[88:91]
	v_mfma_f32_16x16x32_bf16 v[84:87], v[166:169], v[194:197], v[84:87]
	v_mfma_f32_16x16x32_bf16 v[80:83], v[174:177], v[194:197], v[80:83]
	v_mfma_f32_16x16x32_bf16 v[76:79], v[166:169], v[202:205], v[76:79]
	v_mfma_f32_16x16x32_bf16 v[72:75], v[174:177], v[202:205], v[72:75]
	v_mfma_f32_16x16x32_bf16 v[68:71], v[166:169], v[228:231], v[68:71]
	v_mfma_f32_16x16x32_bf16 v[64:67], v[174:177], v[228:231], v[64:67]
	s_setprio 0
	s_barrier
	s_add_i32 s64, s84, s18
	s_add_i32 m0, s64, 0xffffff80
	ds_read_b128 v[178:181], v148 offset:49152
	ds_read_b128 v[182:185], v148 offset:50176
	ds_read_b128 v[190:193], v148 offset:51200
	ds_read_b128 v[194:197], v148 offset:52224
	ds_read_b128 v[198:201], v148 offset:53248
	ds_read_b128 v[202:205], v148 offset:54272
	ds_read_b128 v[206:209], v148 offset:55296
	ds_read_b128 v[228:231], v148 offset:56320
	global_load_lds_dwordx4 v128, s[58:59] offset:128
	s_add_i32 m0, s64, 0x1f80
	s_add_i32 s64, s85, s18
	global_load_lds_dwordx4 v130, s[58:59] offset:128
	s_add_u32 s58, s58, 0x40080
	s_addc_u32 s59, s59, 0
	s_mov_b32 m0, s64
	s_nop 0
	global_load_lds_dwordx4 v128, s[58:59]
	s_add_i32 m0, s64, 0x2000
	s_nop 0
	global_load_lds_dwordx4 v130, s[58:59]
	s_mov_b32 m0, s28
	s_nop 0
	global_load_lds_dwordx4 v134, s[100:101]
	s_mov_b32 m0, s29
	s_nop 0
	global_load_lds_dwordx4 v132, s[100:101]
	s_waitcnt vmcnt(8)
	s_waitcnt lgkmcnt(0)
	s_barrier
	s_setprio 1
	s_waitcnt lgkmcnt(0)
	v_mfma_f32_16x16x32_bf16 v[60:63], v[142:145], v[178:181], v[60:63]
	v_mfma_f32_16x16x32_bf16 v[56:59], v[154:157], v[178:181], v[56:59]
	v_mfma_f32_16x16x32_bf16 v[52:55], v[142:145], v[190:193], v[52:55]
	v_mfma_f32_16x16x32_bf16 v[48:51], v[154:157], v[190:193], v[48:51]
	v_mfma_f32_16x16x32_bf16 v[44:47], v[142:145], v[198:201], v[44:47]
	v_mfma_f32_16x16x32_bf16 v[40:43], v[154:157], v[198:201], v[40:43]
	v_mfma_f32_16x16x32_bf16 v[36:39], v[142:145], v[206:209], v[36:39]
	v_mfma_f32_16x16x32_bf16 v[32:35], v[154:157], v[206:209], v[32:35]
	v_mfma_f32_16x16x32_bf16 v[60:63], v[150:153], v[182:185], v[60:63]
	v_mfma_f32_16x16x32_bf16 v[56:59], v[158:161], v[182:185], v[56:59]
	v_mfma_f32_16x16x32_bf16 v[52:55], v[150:153], v[194:197], v[52:55]
	v_mfma_f32_16x16x32_bf16 v[48:51], v[158:161], v[194:197], v[48:51]
	v_mfma_f32_16x16x32_bf16 v[44:47], v[150:153], v[202:205], v[44:47]
	v_mfma_f32_16x16x32_bf16 v[40:43], v[158:161], v[202:205], v[40:43]
	v_mfma_f32_16x16x32_bf16 v[36:39], v[150:153], v[228:231], v[36:39]
	v_mfma_f32_16x16x32_bf16 v[32:35], v[158:161], v[228:231], v[32:35]
	s_setprio 0
	s_setprio 1
	v_mfma_f32_16x16x32_bf16 v[28:31], v[162:165], v[178:181], v[28:31]
	v_mfma_f32_16x16x32_bf16 v[24:27], v[170:173], v[178:181], v[24:27]
	v_mfma_f32_16x16x32_bf16 v[20:23], v[162:165], v[190:193], v[20:23]
	v_mfma_f32_16x16x32_bf16 v[16:19], v[170:173], v[190:193], v[16:19]
	v_mfma_f32_16x16x32_bf16 v[12:15], v[162:165], v[198:201], v[12:15]
	v_mfma_f32_16x16x32_bf16 v[8:11], v[170:173], v[198:201], v[8:11]
	v_mfma_f32_16x16x32_bf16 v[4:7], v[162:165], v[206:209], v[4:7]
	v_mfma_f32_16x16x32_bf16 v[0:3], v[170:173], v[206:209], v[0:3]
	v_mfma_f32_16x16x32_bf16 v[28:31], v[166:169], v[182:185], v[28:31]
	v_mfma_f32_16x16x32_bf16 v[24:27], v[174:177], v[182:185], v[24:27]
	v_mfma_f32_16x16x32_bf16 v[20:23], v[166:169], v[194:197], v[20:23]
	v_mfma_f32_16x16x32_bf16 v[16:19], v[174:177], v[194:197], v[16:19]
	v_mfma_f32_16x16x32_bf16 v[12:15], v[166:169], v[202:205], v[12:15]
	v_mfma_f32_16x16x32_bf16 v[8:11], v[174:177], v[202:205], v[8:11]
	v_mfma_f32_16x16x32_bf16 v[4:7], v[166:169], v[228:231], v[4:7]
	v_mfma_f32_16x16x32_bf16 v[0:3], v[174:177], v[228:231], v[0:3]
	s_setprio 0
	s_barrier
	s_add_i32 s94, s94, 2
	s_add_u32 s72, s72, 0x100
	s_addc_u32 s73, s73, 0
	s_add_u32 s92, s92, 0x100
	s_addc_u32 s93, s93, 0
	s_cmp_gt_u32 s94, 13
	s_cbranch_scc0 .LBB0_164
	s_and_b64 vcc, exec, s[48:49]
	s_cbranch_vccz .LBB0_167
	s_barrier

; #define PG8_STAGE(bufoff, gbase, voff) do { _Pragma("unroll") for (int _i = 0; _i < 2; ++_i) \
;         __builtin_amdgcn_global_load_lds((const unsigned*)((const char*)(gbase) + (voff)[_i]), (PG8_LAS unsigned*)(lds + (bufoff) + ldsw + _i * 8192), 16, 0, 0); } while (0)
; #define PG8_LDA(dst, b, h) do { _Pragma("unroll") for (int m = 0; m < 4; ++m) _Pragma("unroll") for (int k = 0; k < 2; ++k) dst[m][k] = *(const PG8_LAS bf16x8*)(lds + PG8_SA(b, h) + aoff + m * 2048 + k * 1024); } while (0)
; #define PG8_LDB(dst, b, h) do { _Pragma("unroll") for (int n = 0; n < 2; ++n) _Pragma("unroll") for (int k = 0; k < 2; ++k) dst[n][k] = *(const PG8_LAS bf16x8*)(lds + PG8_SB(b, h) + boff + n * 2048 + k * 1024); } while (0)
; #define PG8_MMA(ai, bj, At, Bt) do { __builtin_amdgcn_s_setprio(1); _Pragma("unroll") for (int m = 0; m < 4; ++m) _Pragma("unroll") for (int n = 0; n < 2; ++n) _Pragma("unroll") for (int k = 0; k < 2; ++k) \
;         acc[ai][bj][m][n] = __builtin_amdgcn_mfma_f32_16x16x32_bf16(Bt[n][k], At[m][k], acc[ai][bj][m][n], 0, 0, 0); __builtin_amdgcn_s_setprio(0); } while (0)
; #define PG8_WAIT_V(n) asm volatile("s_waitcnt vmcnt(" #n ")" ::: "memory")
; #define PG8_BAR __builtin_amdgcn_s_barrier()
; template <class Epi, class Sched, bool ALIGN_EPI = false, bool SP2 = false>
; __device__ __forceinline__ void gemm_phase(PG8_LAS unsigned char* lds, const Gemm g, const Sched& S, const Epi& E) {
;     ...
;         for (int t = 0; t < nt; t += 2) {
;             const bool last = (t == nt - 2);
;             const char* a1 = cA + (size_t)(t + 1) * kstep;
;             const char* a2 = last ? nA : cA + (size_t)(t + 2) * kstep; const char* b2 = last ? nB : cB + (size_t)(t + 2) * kstep;
;             const char* a3 = a2 + kstep; const char* b3 = b2 + kstep;
;             if (last && has_next) S.a_ready(nxt);
;             if constexpr (SP2) {
;             PG8_LDB(B0, 0, 0); PG8_LDB(B1, 0, 1); PG8_SCHED; PG8_LDA(At, 0, 0); PG8_STAGE(PG8_SA(1, 1), a1 + hstep, voffA);
;             PG8_WAIT_V(8); PG8_WAIT_L(0); PG8_BAR; PG8_MMA(0, 0, At, B0); PG8_MMA(0, 1, At, B1); PG8_BAR; PG8_SCHED;
;             PG8_LDA(At, 0, 1); PG8_STAGE(PG8_SB(0, 0), b2, voffB); PG8_STAGE(PG8_SB(0, 1), b2 + hstep, voffB); PG8_STAGE(PG8_SA(0, 0), a2, voffA);
;             PG8_WAIT_V(8); PG8_WAIT_L(0); PG8_BAR; PG8_MMA(1, 0, At, B0); PG8_MMA(1, 1, At, B1); PG8_BAR; PG8_SCHED;
.LBB0_564:
	s_add_u32 s44, vcc_lo, 0xfffc0080
	s_addc_u32 s45, vcc_hi, -1
	s_add_i32 s85, 0, 0x10000
	s_cmp_eq_u32 s84, 12
	s_cselect_b32 s93, s36, s45
	s_cselect_b32 s92, s37, s44
	s_cselect_b32 s59, s67, s94
	s_cselect_b32 s58, s73, s88
	s_add_i32 s8, 0, 0x14000
	v_add_u32_e32 v142, s85, v201
	v_add_u32_e32 v168, s8, v201
	ds_read_b128 v[130:133], v142
	ds_read_b128 v[134:137], v142 offset:1024
	ds_read_b128 v[138:141], v142 offset:2048
	ds_read_b128 v[142:145], v142 offset:3072
	ds_read_b128 v[156:159], v168
	ds_read_b128 v[160:163], v168 offset:1024
	ds_read_b128 v[164:167], v168 offset:2048
	ds_read_b128 v[168:171], v168 offset:3072
	s_add_i32 m0, s15, 0xc000
	ds_read_b128 v[172:175], v203
	ds_read_b128 v[176:179], v203 offset:1024
	ds_read_b128 v[180:183], v203 offset:2048
	ds_read_b128 v[184:187], v203 offset:3072
	ds_read_b128 v[188:191], v203 offset:4096
	ds_read_b128 v[192:195], v203 offset:5120
	ds_read_b128 v[196:199], v203 offset:6144
	ds_read_b128 v[204:207], v203 offset:7168
	global_load_lds_dwordx4 v152, vcc
	s_add_i32 m0, s15, 0xe000
	s_nop 0
	global_load_lds_dwordx4 v154, vcc
	s_waitcnt vmcnt(8)
	s_waitcnt lgkmcnt(0)
	s_barrier
	s_setprio 1
	s_waitcnt lgkmcnt(0)
	v_mfma_f32_16x16x32_bf16 v[124:127], v[130:133], v[172:175], v[124:127]
	v_mfma_f32_16x16x32_bf16 v[120:123], v[138:141], v[172:175], v[120:123]
	v_mfma_f32_16x16x32_bf16 v[108:111], v[130:133], v[180:183], v[108:111]
	v_mfma_f32_16x16x32_bf16 v[104:107], v[138:141], v[180:183], v[104:107]
	v_mfma_f32_16x16x32_bf16 v[92:95], v[130:133], v[188:191], v[92:95]
	v_mfma_f32_16x16x32_bf16 v[88:91], v[138:141], v[188:191], v[88:91]
	v_mfma_f32_16x16x32_bf16 v[76:79], v[130:133], v[196:199], v[76:79]
	v_mfma_f32_16x16x32_bf16 v[72:75], v[138:141], v[196:199], v[72:75]
	v_mfma_f32_16x16x32_bf16 v[124:127], v[134:137], v[176:179], v[124:127]
	v_mfma_f32_16x16x32_bf16 v[120:123], v[142:145], v[176:179], v[120:123]
	v_mfma_f32_16x16x32_bf16 v[108:111], v[134:137], v[184:187], v[108:111]
	v_mfma_f32_16x16x32_bf16 v[104:107], v[142:145], v[184:187], v[104:107]
	v_mfma_f32_16x16x32_bf16 v[92:95], v[134:137], v[192:195], v[92:95]
	v_mfma_f32_16x16x32_bf16 v[88:91], v[142:145], v[192:195], v[88:91]
	v_mfma_f32_16x16x32_bf16 v[76:79], v[134:137], v[204:207], v[76:79]
	v_mfma_f32_16x16x32_bf16 v[72:75], v[142:145], v[204:207], v[72:75]
	s_setprio 0
	s_setprio 1
	v_mfma_f32_16x16x32_bf16 v[116:119], v[156:159], v[172:175], v[116:119]
	v_mfma_f32_16x16x32_bf16 v[112:115], v[164:167], v[172:175], v[112:115]
	v_mfma_f32_16x16x32_bf16 v[100:103], v[156:159], v[180:183], v[100:103]
	v_mfma_f32_16x16x32_bf16 v[96:99], v[164:167], v[180:183], v[96:99]
	v_mfma_f32_16x16x32_bf16 v[84:87], v[156:159], v[188:191], v[84:87]
	v_mfma_f32_16x16x32_bf16 v[80:83], v[164:167], v[188:191], v[80:83]
	v_mfma_f32_16x16x32_bf16 v[68:71], v[156:159], v[196:199], v[68:71]
	v_mfma_f32_16x16x32_bf16 v[64:67], v[164:167], v[196:199], v[64:67]
	v_mfma_f32_16x16x32_bf16 v[116:119], v[160:163], v[176:179], v[116:119]
	v_mfma_f32_16x16x32_bf16 v[112:115], v[168:171], v[176:179], v[112:115]
	v_mfma_f32_16x16x32_bf16 v[100:103], v[160:163], v[184:187], v[100:103]
	v_mfma_f32_16x16x32_bf16 v[96:99], v[168:171], v[184:187], v[96:99]
	v_mfma_f32_16x16x32_bf16 v[84:87], v[160:163], v[192:195], v[84:87]
	v_mfma_f32_16x16x32_bf16 v[80:83], v[168:171], v[192:195], v[80:83]
	v_mfma_f32_16x16x32_bf16 v[68:71], v[160:163], v[204:207], v[68:71]
	v_mfma_f32_16x16x32_bf16 v[64:67], v[168:171], v[204:207], v[64:67]
	s_setprio 0
	s_barrier
	s_add_i32 s44, s85, s14
	s_mov_b32 m0, s44
	ds_read_b128 v[172:175], v203 offset:16384
	ds_read_b128 v[176:179], v203 offset:17408
	ds_read_b128 v[180:183], v203 offset:18432
	ds_read_b128 v[184:187], v203 offset:19456
	ds_read_b128 v[188:191], v203 offset:20480
	ds_read_b128 v[192:195], v203 offset:21504
	ds_read_b128 v[196:199], v203 offset:22528
	ds_read_b128 v[204:207], v203 offset:23552
	global_load_lds_dwordx4 v128, s[58:59]
	s_add_i32 m0, s44, 0x2000
	s_add_u32 s44, s58, 0x40000
	s_addc_u32 s45, s59, 0
	s_add_i32 s8, s8, s14
	global_load_lds_dwordx4 v146, s[58:59]
	s_mov_b32 m0, s8
	s_nop 0
	global_load_lds_dwordx4 v128, s[44:45]
	s_add_i32 m0, s8, 0x2000
	s_nop 0
	global_load_lds_dwordx4 v146, s[44:45]
	s_mov_b32 m0, s15
	s_nop 0
	global_load_lds_dwordx4 v150, s[92:93]
	s_mov_b32 m0, s17
	s_nop 0
	global_load_lds_dwordx4 v148, s[92:93]
	s_waitcnt vmcnt(8)
	s_waitcnt lgkmcnt(0)
	s_barrier
	s_setprio 1
	s_waitcnt lgkmcnt(0)
	v_mfma_f32_16x16x32_bf16 v[60:63], v[130:133], v[172:175], v[60:63]
	v_mfma_f32_16x16x32_bf16 v[56:59], v[138:141], v[172:175], v[56:59]
	v_mfma_f32_16x16x32_bf16 v[44:47], v[130:133], v[180:183], v[44:47]
	v_mfma_f32_16x16x32_bf16 v[40:43], v[138:141], v[180:183], v[40:43]
	v_mfma_f32_16x16x32_bf16 v[28:31], v[130:133], v[188:191], v[28:31]
	v_mfma_f32_16x16x32_bf16 v[24:27], v[138:141], v[188:191], v[24:27]
	v_mfma_f32_16x16x32_bf16 v[12:15], v[130:133], v[196:199], v[12:15]
	v_mfma_f32_16x16x32_bf16 v[8:11], v[138:141], v[196:199], v[8:11]
	v_mfma_f32_16x16x32_bf16 v[60:63], v[134:137], v[176:179], v[60:63]
	v_mfma_f32_16x16x32_bf16 v[56:59], v[142:145], v[176:179], v[56:59]
	v_mfma_f32_16x16x32_bf16 v[44:47], v[134:137], v[184:187], v[44:47]
	v_mfma_f32_16x16x32_bf16 v[40:43], v[142:145], v[184:187], v[40:43]
	v_mfma_f32_16x16x32_bf16 v[28:31], v[134:137], v[192:195], v[28:31]
	v_mfma_f32_16x16x32_bf16 v[24:27], v[142:145], v[192:195], v[24:27]
	v_mfma_f32_16x16x32_bf16 v[12:15], v[134:137], v[204:207], v[12:15]
	v_mfma_f32_16x16x32_bf16 v[8:11], v[142:145], v[204:207], v[8:11]
	s_setprio 0
	s_setprio 1
	v_mfma_f32_16x16x32_bf16 v[52:55], v[156:159], v[172:175], v[52:55]
	v_mfma_f32_16x16x32_bf16 v[48:51], v[164:167], v[172:175], v[48:51]
	v_mfma_f32_16x16x32_bf16 v[36:39], v[156:159], v[180:183], v[36:39]
	v_mfma_f32_16x16x32_bf16 v[32:35], v[164:167], v[180:183], v[32:35]
	v_mfma_f32_16x16x32_bf16 v[20:23], v[156:159], v[188:191], v[20:23]
	v_mfma_f32_16x16x32_bf16 v[16:19], v[164:167], v[188:191], v[16:19]
	v_mfma_f32_16x16x32_bf16 v[4:7], v[156:159], v[196:199], v[4:7]
	v_mfma_f32_16x16x32_bf16 v[0:3], v[164:167], v[196:199], v[0:3]
	v_mfma_f32_16x16x32_bf16 v[52:55], v[160:163], v[176:179], v[52:55]
	v_mfma_f32_16x16x32_bf16 v[48:51], v[168:171], v[176:179], v[48:51]
	v_mfma_f32_16x16x32_bf16 v[36:39], v[160:163], v[184:187], v[36:39]
	v_mfma_f32_16x16x32_bf16 v[32:35], v[168:171], v[184:187], v[32:35]
	v_mfma_f32_16x16x32_bf16 v[20:23], v[160:163], v[192:195], v[20:23]
	v_mfma_f32_16x16x32_bf16 v[16:19], v[168:171], v[192:195], v[16:19]
	v_mfma_f32_16x16x32_bf16 v[4:7], v[160:163], v[204:207], v[4:7]
	v_mfma_f32_16x16x32_bf16 v[0:3], v[168:171], v[204:207], v[0:3]
	s_setprio 0
	s_barrier
; #define PG8_STAGE(bufoff, gbase, voff) do { _Pragma("unroll") for (int _i = 0; _i < 2; ++_i) \
;         __builtin_amdgcn_global_load_lds((const unsigned*)((const char*)(gbase) + (voff)[_i]), (PG8_LAS unsigned*)(lds + (bufoff) + ldsw + _i * 8192), 16, 0, 0); } while (0)
; #define PG8_LDA(dst, b, h) do { _Pragma("unroll") for (int m = 0; m < 4; ++m) _Pragma("unroll") for (int k = 0; k < 2; ++k) dst[m][k] = *(const PG8_LAS bf16x8*)(lds + PG8_SA(b, h) + aoff + m * 2048 + k * 1024); } while (0)
; #define PG8_LDB(dst, b, h) do { _Pragma("unroll") for (int n = 0; n < 2; ++n) _Pragma("unroll") for (int k = 0; k < 2; ++k) dst[n][k] = *(const PG8_LAS bf16x8*)(lds + PG8_SB(b, h) + boff + n * 2048 + k * 1024); } while (0)
; #define PG8_MMA(ai, bj, At, Bt) do { __builtin_amdgcn_s_setprio(1); _Pragma("unroll") for (int m = 0; m < 4; ++m) _Pragma("unroll") for (int n = 0; n < 2; ++n) _Pragma("unroll") for (int k = 0; k < 2; ++k) \
;         acc[ai][bj][m][n] = __builtin_amdgcn_mfma_f32_16x16x32_bf16(Bt[n][k], At[m][k], acc[ai][bj][m][n], 0, 0, 0); __builtin_amdgcn_s_setprio(0); } while (0)
; #define PG8_WAIT_V(n) asm volatile("s_waitcnt vmcnt(" #n ")" ::: "memory")
; #define PG8_WAIT_L(n) asm volatile("s_waitcnt lgkmcnt(" #n ")" ::: "memory")
; #define PG8_BAR __builtin_amdgcn_s_barrier()
; #define PG8_SCHED __builtin_amdgcn_sched_barrier(0)
; template <class Epi, class Sched, bool ALIGN_EPI = false, bool SP2 = false>
; __device__ __forceinline__ void gemm_phase(PG8_LAS unsigned char* lds, const Gemm g, const Sched& S, const Epi& E) {
;     ...
;             PG8_LDB(B0, 1, 0); PG8_LDB(B1, 1, 1); PG8_SCHED; PG8_LDA(At, 1, 0); PG8_STAGE(PG8_SA(0, 1), a2 + hstep, voffA);
;             PG8_WAIT_V(8); PG8_WAIT_L(0); PG8_BAR; PG8_MMA(0, 0, At, B0); PG8_MMA(0, 1, At, B1); PG8_BAR; PG8_SCHED;
;             PG8_LDA(At, 1, 1); PG8_STAGE(PG8_SB(1, 0), b3, voffB); PG8_STAGE(PG8_SB(1, 1), b3 + hstep, voffB); PG8_STAGE(PG8_SA(1, 0), a3, voffA);
;             PG8_WAIT_V(8); PG8_WAIT_L(0); PG8_BAR; PG8_MMA(1, 0, At, B0); PG8_MMA(1, 1, At, B1); PG8_BAR; PG8_SCHED;
	s_add_i32 s8, 0, 0x18000
	s_add_i32 s85, 0, 0x1c000
	v_add_u32_e32 v142, s8, v201
	v_add_u32_e32 v168, s85, v201
	ds_read_b128 v[130:133], v142
	ds_read_b128 v[134:137], v142 offset:1024
	ds_read_b128 v[138:141], v142 offset:2048
	ds_read_b128 v[142:145], v142 offset:3072
	ds_read_b128 v[156:159], v168
	ds_read_b128 v[160:163], v168 offset:1024
	ds_read_b128 v[164:167], v168 offset:2048
	ds_read_b128 v[168:171], v168 offset:3072
	s_add_u32 s44, s92, 0x40000
	s_addc_u32 s45, s93, 0
	s_mov_b32 m0, s18
	ds_read_b128 v[172:175], v203 offset:32768
	ds_read_b128 v[176:179], v203 offset:33792
	ds_read_b128 v[180:183], v203 offset:34816
	ds_read_b128 v[184:187], v203 offset:35840
	ds_read_b128 v[188:191], v203 offset:36864
	ds_read_b128 v[192:195], v203 offset:37888
	ds_read_b128 v[196:199], v203 offset:38912
	ds_read_b128 v[204:207], v203 offset:39936
	global_load_lds_dwordx4 v150, s[44:45]
	s_mov_b32 m0, s19
	s_nop 0
	global_load_lds_dwordx4 v148, s[44:45]
	s_waitcnt vmcnt(8)
	s_waitcnt lgkmcnt(0)
	s_barrier
	s_setprio 1
	s_waitcnt lgkmcnt(0)
	v_mfma_f32_16x16x32_bf16 v[124:127], v[130:133], v[172:175], v[124:127]
	v_mfma_f32_16x16x32_bf16 v[120:123], v[138:141], v[172:175], v[120:123]
	v_mfma_f32_16x16x32_bf16 v[108:111], v[130:133], v[180:183], v[108:111]
	v_mfma_f32_16x16x32_bf16 v[104:107], v[138:141], v[180:183], v[104:107]
	v_mfma_f32_16x16x32_bf16 v[92:95], v[130:133], v[188:191], v[92:95]
	v_mfma_f32_16x16x32_bf16 v[88:91], v[138:141], v[188:191], v[88:91]
	v_mfma_f32_16x16x32_bf16 v[76:79], v[130:133], v[196:199], v[76:79]
	v_mfma_f32_16x16x32_bf16 v[72:75], v[138:141], v[196:199], v[72:75]
	v_mfma_f32_16x16x32_bf16 v[124:127], v[134:137], v[176:179], v[124:127]
	v_mfma_f32_16x16x32_bf16 v[120:123], v[142:145], v[176:179], v[120:123]
	v_mfma_f32_16x16x32_bf16 v[108:111], v[134:137], v[184:187], v[108:111]
	v_mfma_f32_16x16x32_bf16 v[104:107], v[142:145], v[184:187], v[104:107]
	v_mfma_f32_16x16x32_bf16 v[92:95], v[134:137], v[192:195], v[92:95]
	v_mfma_f32_16x16x32_bf16 v[88:91], v[142:145], v[192:195], v[88:91]
	v_mfma_f32_16x16x32_bf16 v[76:79], v[134:137], v[204:207], v[76:79]
	v_mfma_f32_16x16x32_bf16 v[72:75], v[142:145], v[204:207], v[72:75]
	s_setprio 0
	s_setprio 1
	v_mfma_f32_16x16x32_bf16 v[116:119], v[156:159], v[172:175], v[116:119]
	v_mfma_f32_16x16x32_bf16 v[112:115], v[164:167], v[172:175], v[112:115]
	v_mfma_f32_16x16x32_bf16 v[100:103], v[156:159], v[180:183], v[100:103]
	v_mfma_f32_16x16x32_bf16 v[96:99], v[164:167], v[180:183], v[96:99]
	v_mfma_f32_16x16x32_bf16 v[84:87], v[156:159], v[188:191], v[84:87]
	v_mfma_f32_16x16x32_bf16 v[80:83], v[164:167], v[188:191], v[80:83]
	v_mfma_f32_16x16x32_bf16 v[68:71], v[156:159], v[196:199], v[68:71]
	v_mfma_f32_16x16x32_bf16 v[64:67], v[164:167], v[196:199], v[64:67]
	v_mfma_f32_16x16x32_bf16 v[116:119], v[160:163], v[176:179], v[116:119]
	v_mfma_f32_16x16x32_bf16 v[112:115], v[168:171], v[176:179], v[112:115]
	v_mfma_f32_16x16x32_bf16 v[100:103], v[160:163], v[184:187], v[100:103]
	v_mfma_f32_16x16x32_bf16 v[96:99], v[168:171], v[184:187], v[96:99]
	v_mfma_f32_16x16x32_bf16 v[84:87], v[160:163], v[192:195], v[84:87]
	v_mfma_f32_16x16x32_bf16 v[80:83], v[168:171], v[192:195], v[80:83]
	v_mfma_f32_16x16x32_bf16 v[68:71], v[160:163], v[204:207], v[68:71]
	v_mfma_f32_16x16x32_bf16 v[64:67], v[168:171], v[204:207], v[64:67]
	s_setprio 0
	s_barrier
	s_add_i32 s8, s8, s14
	s_add_i32 m0, s8, 0xffffff80
	ds_read_b128 v[172:175], v203 offset:49152
	ds_read_b128 v[176:179], v203 offset:50176
	ds_read_b128 v[180:183], v203 offset:51200
	ds_read_b128 v[184:187], v203 offset:52224
	ds_read_b128 v[188:191], v203 offset:53248
	ds_read_b128 v[192:195], v203 offset:54272
	ds_read_b128 v[196:199], v203 offset:55296
	ds_read_b128 v[204:207], v203 offset:56320
	global_load_lds_dwordx4 v128, s[58:59] offset:128
	s_add_i32 m0, s8, 0x1f80
	s_add_u32 s44, s58, 0x40080
	s_addc_u32 s45, s59, 0
	s_add_i32 s8, s85, s14
	global_load_lds_dwordx4 v146, s[58:59] offset:128
	s_mov_b32 m0, s8
	s_nop 0
	global_load_lds_dwordx4 v128, s[44:45]
	s_add_i32 m0, s8, 0x2000
	s_nop 0
	global_load_lds_dwordx4 v146, s[44:45]
	s_add_i32 m0, s30, 0xffffff80
	s_nop 0
	global_load_lds_dwordx4 v150, s[92:93] offset:128
	s_add_i32 m0, s31, 0xffffff80
	s_nop 0
	global_load_lds_dwordx4 v148, s[92:93] offset:128
	s_waitcnt vmcnt(8)
	s_waitcnt lgkmcnt(0)
	s_barrier
	s_setprio 1
	s_waitcnt lgkmcnt(0)
	v_mfma_f32_16x16x32_bf16 v[60:63], v[130:133], v[172:175], v[60:63]
	v_mfma_f32_16x16x32_bf16 v[56:59], v[138:141], v[172:175], v[56:59]
	v_mfma_f32_16x16x32_bf16 v[44:47], v[130:133], v[180:183], v[44:47]
	v_mfma_f32_16x16x32_bf16 v[40:43], v[138:141], v[180:183], v[40:43]
	v_mfma_f32_16x16x32_bf16 v[28:31], v[130:133], v[188:191], v[28:31]
	v_mfma_f32_16x16x32_bf16 v[24:27], v[138:141], v[188:191], v[24:27]
	v_mfma_f32_16x16x32_bf16 v[12:15], v[130:133], v[196:199], v[12:15]
	v_mfma_f32_16x16x32_bf16 v[8:11], v[138:141], v[196:199], v[8:11]
	v_mfma_f32_16x16x32_bf16 v[60:63], v[134:137], v[176:179], v[60:63]
	v_mfma_f32_16x16x32_bf16 v[56:59], v[142:145], v[176:179], v[56:59]
	v_mfma_f32_16x16x32_bf16 v[44:47], v[134:137], v[184:187], v[44:47]
	v_mfma_f32_16x16x32_bf16 v[40:43], v[142:145], v[184:187], v[40:43]
	v_mfma_f32_16x16x32_bf16 v[28:31], v[134:137], v[192:195], v[28:31]
	v_mfma_f32_16x16x32_bf16 v[24:27], v[142:145], v[192:195], v[24:27]
	v_mfma_f32_16x16x32_bf16 v[12:15], v[134:137], v[204:207], v[12:15]
	v_mfma_f32_16x16x32_bf16 v[8:11], v[142:145], v[204:207], v[8:11]
	s_setprio 0
	s_setprio 1
	v_mfma_f32_16x16x32_bf16 v[52:55], v[156:159], v[172:175], v[52:55]
	v_mfma_f32_16x16x32_bf16 v[48:51], v[164:167], v[172:175], v[48:51]
	v_mfma_f32_16x16x32_bf16 v[36:39], v[156:159], v[180:183], v[36:39]
	v_mfma_f32_16x16x32_bf16 v[32:35], v[164:167], v[180:183], v[32:35]
	v_mfma_f32_16x16x32_bf16 v[20:23], v[156:159], v[188:191], v[20:23]
	v_mfma_f32_16x16x32_bf16 v[16:19], v[164:167], v[188:191], v[16:19]
	v_mfma_f32_16x16x32_bf16 v[4:7], v[156:159], v[196:199], v[4:7]
	v_mfma_f32_16x16x32_bf16 v[0:3], v[164:167], v[196:199], v[0:3]
	v_mfma_f32_16x16x32_bf16 v[52:55], v[160:163], v[176:179], v[52:55]
	v_mfma_f32_16x16x32_bf16 v[48:51], v[168:171], v[176:179], v[48:51]
	v_mfma_f32_16x16x32_bf16 v[36:39], v[160:163], v[184:187], v[36:39]
	v_mfma_f32_16x16x32_bf16 v[32:35], v[168:171], v[184:187], v[32:35]
	v_mfma_f32_16x16x32_bf16 v[20:23], v[160:163], v[192:195], v[20:23]
	v_mfma_f32_16x16x32_bf16 v[16:19], v[168:171], v[192:195], v[16:19]
	v_mfma_f32_16x16x32_bf16 v[4:7], v[160:163], v[204:207], v[4:7]
	v_mfma_f32_16x16x32_bf16 v[0:3], v[168:171], v[204:207], v[0:3]
	s_setprio 0
	s_barrier
	s_add_i32 s84, s84, 2
	s_add_u32 vcc_lo, vcc_lo, 0x100
	s_addc_u32 vcc_hi, vcc_hi, 0
	s_add_u32 s88, s88, 0x100
	s_addc_u32 s94, s94, 0
	s_cmp_gt_u32 s84, 13
	s_cbranch_scc0 .LBB0_564
	s_and_b64 vcc, exec, s[62:63]
	s_cbranch_vccz .LBB0_567
	s_barrier

; #define PG8_STAGE(bufoff, gbase, voff) do { _Pragma("unroll") for (int _i = 0; _i < 2; ++_i) \
;         __builtin_amdgcn_global_load_lds((const unsigned*)((const char*)(gbase) + (voff)[_i]), (PG8_LAS unsigned*)(lds + (bufoff) + ldsw + _i * 8192), 16, 0, 0); } while (0)
; #define PG8_LDA(dst, b, h) do { _Pragma("unroll") for (int m = 0; m < 4; ++m) _Pragma("unroll") for (int k = 0; k < 2; ++k) dst[m][k] = *(const PG8_LAS bf16x8*)(lds + PG8_SA(b, h) + aoff + m * 2048 + k * 1024); } while (0)
; #define PG8_LDB(dst, b, h) do { _Pragma("unroll") for (int n = 0; n < 2; ++n) _Pragma("unroll") for (int k = 0; k < 2; ++k) dst[n][k] = *(const PG8_LAS bf16x8*)(lds + PG8_SB(b, h) + boff + n * 2048 + k * 1024); } while (0)
; #define PG8_MMA(ai, bj, At, Bt) do { __builtin_amdgcn_s_setprio(1); _Pragma("unroll") for (int m = 0; m < 4; ++m) _Pragma("unroll") for (int n = 0; n < 2; ++n) _Pragma("unroll") for (int k = 0; k < 2; ++k) \
;         acc[ai][bj][m][n] = __builtin_amdgcn_mfma_f32_16x16x32_bf16(Bt[n][k], At[m][k], acc[ai][bj][m][n], 0, 0, 0); __builtin_amdgcn_s_setprio(0); } while (0)
; #define PG8_WAIT_V(n) asm volatile("s_waitcnt vmcnt(" #n ")" ::: "memory")
; #define PG8_BAR __builtin_amdgcn_s_barrier()
; template <class Epi, class Sched, bool ALIGN_EPI = false, bool SP2 = false>
; __device__ __forceinline__ void gemm_phase(PG8_LAS unsigned char* lds, const Gemm g, const Sched& S, const Epi& E) {
;     ...
;         for (int t = 0; t < nt; t += 2) {
;             const bool last = (t == nt - 2);
;             const char* a1 = cA + (size_t)(t + 1) * kstep;
;             const char* a2 = last ? nA : cA + (size_t)(t + 2) * kstep; const char* b2 = last ? nB : cB + (size_t)(t + 2) * kstep;
;             const char* a3 = a2 + kstep; const char* b3 = b2 + kstep;
;             if (last && has_next) S.a_ready(nxt);
;             if constexpr (SP2) {
;             PG8_LDB(B0, 0, 0); PG8_LDB(B1, 0, 1); PG8_SCHED; PG8_LDA(At, 0, 0); PG8_STAGE(PG8_SA(1, 1), a1 + hstep, voffA);
;             PG8_WAIT_V(8); PG8_WAIT_L(0); PG8_BAR; PG8_MMA(0, 0, At, B0); PG8_MMA(0, 1, At, B1); PG8_BAR; PG8_SCHED;
;             PG8_LDA(At, 0, 1); PG8_STAGE(PG8_SB(0, 0), b2, voffB); PG8_STAGE(PG8_SB(0, 1), b2 + hstep, voffB); PG8_STAGE(PG8_SA(0, 0), a2, voffA);
;             PG8_WAIT_V(8); PG8_WAIT_L(0); PG8_BAR; PG8_MMA(1, 0, At, B0); PG8_MMA(1, 1, At, B1); PG8_BAR; PG8_SCHED;
.LBB0_598:
	s_add_u32 s58, vcc_lo, 0xfffc0080
	s_addc_u32 s59, vcc_hi, -1
	s_add_i32 s84, 0, 0x10000
	s_cmp_eq_u32 s94, 12
	s_cselect_b32 s65, s35, s59
	s_cselect_b32 s64, s36, s58
	s_cselect_b32 s59, s37, s93
	s_cselect_b32 s58, s43, s88
	s_add_i32 s97, 0, 0x14000
	v_add_u32_e32 v76, s84, v228
	v_add_u32_e32 v168, s97, v228
	ds_read_b128 v[64:67], v76
	ds_read_b128 v[68:71], v76 offset:1024
	ds_read_b128 v[72:75], v76 offset:2048
	ds_read_b128 v[76:79], v76 offset:3072
	ds_read_b128 v[156:159], v168
	ds_read_b128 v[160:163], v168 offset:1024
	ds_read_b128 v[164:167], v168 offset:2048
	ds_read_b128 v[168:171], v168 offset:3072
	s_add_i32 m0, s18, 0xc000
	ds_read_b128 v[172:175], v230
	ds_read_b128 v[176:179], v230 offset:1024
	ds_read_b128 v[180:183], v230 offset:2048
	ds_read_b128 v[184:187], v230 offset:3072
	ds_read_b128 v[188:191], v230 offset:4096
	ds_read_b128 v[192:195], v230 offset:5120
	ds_read_b128 v[196:199], v230 offset:6144
	ds_read_b128 v[200:203], v230 offset:7168
	global_load_lds_dwordx4 v152, vcc
	s_add_i32 m0, s18, 0xe000
	s_nop 0
	global_load_lds_dwordx4 v154, vcc
	s_waitcnt vmcnt(8)
	s_waitcnt lgkmcnt(0)
	s_barrier
	s_setprio 1
	s_waitcnt lgkmcnt(0)
	v_mfma_f32_16x16x32_bf16 v[142:145], v[64:67], v[172:175], v[142:145]
	v_mfma_f32_16x16x32_bf16 v[138:141], v[72:75], v[172:175], v[138:141]
	v_mfma_f32_16x16x32_bf16 v[134:137], v[64:67], v[180:183], v[134:137]
	v_mfma_f32_16x16x32_bf16 v[124:127], v[72:75], v[180:183], v[124:127]
	v_mfma_f32_16x16x32_bf16 v[108:111], v[64:67], v[188:191], v[108:111]
	v_mfma_f32_16x16x32_bf16 v[104:107], v[72:75], v[188:191], v[104:107]
	v_mfma_f32_16x16x32_bf16 v[100:103], v[64:67], v[196:199], v[100:103]
	v_mfma_f32_16x16x32_bf16 v[92:95], v[72:75], v[196:199], v[92:95]
	v_mfma_f32_16x16x32_bf16 v[142:145], v[68:71], v[176:179], v[142:145]
	v_mfma_f32_16x16x32_bf16 v[138:141], v[76:79], v[176:179], v[138:141]
	v_mfma_f32_16x16x32_bf16 v[134:137], v[68:71], v[184:187], v[134:137]
	v_mfma_f32_16x16x32_bf16 v[124:127], v[76:79], v[184:187], v[124:127]
	v_mfma_f32_16x16x32_bf16 v[108:111], v[68:71], v[192:195], v[108:111]
	v_mfma_f32_16x16x32_bf16 v[104:107], v[76:79], v[192:195], v[104:107]
	v_mfma_f32_16x16x32_bf16 v[100:103], v[68:71], v[200:203], v[100:103]
	v_mfma_f32_16x16x32_bf16 v[92:95], v[76:79], v[200:203], v[92:95]
	s_setprio 0
	s_setprio 1
	v_mfma_f32_16x16x32_bf16 v[130:133], v[156:159], v[172:175], v[130:133]
	v_mfma_f32_16x16x32_bf16 v[120:123], v[164:167], v[172:175], v[120:123]
	v_mfma_f32_16x16x32_bf16 v[116:119], v[156:159], v[180:183], v[116:119]
	v_mfma_f32_16x16x32_bf16 v[112:115], v[164:167], v[180:183], v[112:115]
	v_mfma_f32_16x16x32_bf16 v[96:99], v[156:159], v[188:191], v[96:99]
	v_mfma_f32_16x16x32_bf16 v[88:91], v[164:167], v[188:191], v[88:91]
	v_mfma_f32_16x16x32_bf16 v[84:87], v[156:159], v[196:199], v[84:87]
	v_mfma_f32_16x16x32_bf16 v[80:83], v[164:167], v[196:199], v[80:83]
	v_mfma_f32_16x16x32_bf16 v[130:133], v[160:163], v[176:179], v[130:133]
	v_mfma_f32_16x16x32_bf16 v[120:123], v[168:171], v[176:179], v[120:123]
	v_mfma_f32_16x16x32_bf16 v[116:119], v[160:163], v[184:187], v[116:119]
	v_mfma_f32_16x16x32_bf16 v[112:115], v[168:171], v[184:187], v[112:115]
	v_mfma_f32_16x16x32_bf16 v[96:99], v[160:163], v[192:195], v[96:99]
	v_mfma_f32_16x16x32_bf16 v[88:91], v[168:171], v[192:195], v[88:91]
	v_mfma_f32_16x16x32_bf16 v[84:87], v[160:163], v[200:203], v[84:87]
	v_mfma_f32_16x16x32_bf16 v[80:83], v[168:171], v[200:203], v[80:83]
	s_setprio 0
	s_barrier
	s_add_i32 s84, s84, s17
	s_mov_b32 m0, s84
	ds_read_b128 v[172:175], v230 offset:16384
	ds_read_b128 v[176:179], v230 offset:17408
	ds_read_b128 v[180:183], v230 offset:18432
	ds_read_b128 v[184:187], v230 offset:19456
	ds_read_b128 v[188:191], v230 offset:20480
	ds_read_b128 v[192:195], v230 offset:21504
	ds_read_b128 v[196:199], v230 offset:22528
	ds_read_b128 v[200:203], v230 offset:23552
	global_load_lds_dwordx4 v128, s[58:59]
	s_add_i32 m0, s84, 0x2000
	s_add_u32 s84, s58, 0x40000
	s_addc_u32 s85, s59, 0
	s_add_i32 s97, s97, s17
	global_load_lds_dwordx4 v146, s[58:59]
	s_mov_b32 m0, s97
	s_nop 0
	global_load_lds_dwordx4 v128, s[84:85]
	s_add_i32 m0, s97, 0x2000
	s_nop 0
	global_load_lds_dwordx4 v146, s[84:85]
	s_mov_b32 m0, s18
	s_nop 0
	global_load_lds_dwordx4 v150, s[64:65]
	s_mov_b32 m0, s19
	s_nop 0
	global_load_lds_dwordx4 v148, s[64:65]
	s_add_u32 s100, s64, 0x80
	s_addc_u32 s101, s65, 0
	s_waitcnt vmcnt(8)
	s_waitcnt lgkmcnt(0)
	s_barrier
	s_setprio 1
	s_waitcnt lgkmcnt(0)
	v_mfma_f32_16x16x32_bf16 v[60:63], v[64:67], v[172:175], v[60:63]
	v_mfma_f32_16x16x32_bf16 v[56:59], v[72:75], v[172:175], v[56:59]
	v_mfma_f32_16x16x32_bf16 v[52:55], v[64:67], v[180:183], v[52:55]
	v_mfma_f32_16x16x32_bf16 v[44:47], v[72:75], v[180:183], v[44:47]
	v_mfma_f32_16x16x32_bf16 v[28:31], v[64:67], v[188:191], v[28:31]
	v_mfma_f32_16x16x32_bf16 v[24:27], v[72:75], v[188:191], v[24:27]
	v_mfma_f32_16x16x32_bf16 v[12:15], v[64:67], v[196:199], v[12:15]
	v_mfma_f32_16x16x32_bf16 v[8:11], v[72:75], v[196:199], v[8:11]
	v_mfma_f32_16x16x32_bf16 v[60:63], v[68:71], v[176:179], v[60:63]
	v_mfma_f32_16x16x32_bf16 v[56:59], v[76:79], v[176:179], v[56:59]
	v_mfma_f32_16x16x32_bf16 v[52:55], v[68:71], v[184:187], v[52:55]
	v_mfma_f32_16x16x32_bf16 v[44:47], v[76:79], v[184:187], v[44:47]
	v_mfma_f32_16x16x32_bf16 v[28:31], v[68:71], v[192:195], v[28:31]
	v_mfma_f32_16x16x32_bf16 v[24:27], v[76:79], v[192:195], v[24:27]
	v_mfma_f32_16x16x32_bf16 v[12:15], v[68:71], v[200:203], v[12:15]
	v_mfma_f32_16x16x32_bf16 v[8:11], v[76:79], v[200:203], v[8:11]
	s_setprio 0
	s_setprio 1
	v_mfma_f32_16x16x32_bf16 v[48:51], v[156:159], v[172:175], v[48:51]
	v_mfma_f32_16x16x32_bf16 v[40:43], v[164:167], v[172:175], v[40:43]
	v_mfma_f32_16x16x32_bf16 v[36:39], v[156:159], v[180:183], v[36:39]
	v_mfma_f32_16x16x32_bf16 v[32:35], v[164:167], v[180:183], v[32:35]
	v_mfma_f32_16x16x32_bf16 v[20:23], v[156:159], v[188:191], v[20:23]
	v_mfma_f32_16x16x32_bf16 v[16:19], v[164:167], v[188:191], v[16:19]
	v_mfma_f32_16x16x32_bf16 v[4:7], v[156:159], v[196:199], v[4:7]
	v_mfma_f32_16x16x32_bf16 v[0:3], v[164:167], v[196:199], v[0:3]
	v_mfma_f32_16x16x32_bf16 v[48:51], v[160:163], v[176:179], v[48:51]
	v_mfma_f32_16x16x32_bf16 v[40:43], v[168:171], v[176:179], v[40:43]
	v_mfma_f32_16x16x32_bf16 v[36:39], v[160:163], v[184:187], v[36:39]
	v_mfma_f32_16x16x32_bf16 v[32:35], v[168:171], v[184:187], v[32:35]
	v_mfma_f32_16x16x32_bf16 v[20:23], v[160:163], v[192:195], v[20:23]
	v_mfma_f32_16x16x32_bf16 v[16:19], v[168:171], v[192:195], v[16:19]
	v_mfma_f32_16x16x32_bf16 v[4:7], v[160:163], v[200:203], v[4:7]
	v_mfma_f32_16x16x32_bf16 v[0:3], v[168:171], v[200:203], v[0:3]
	s_setprio 0
	s_barrier
; #define PG8_STAGE(bufoff, gbase, voff) do { _Pragma("unroll") for (int _i = 0; _i < 2; ++_i) \
;         __builtin_amdgcn_global_load_lds((const unsigned*)((const char*)(gbase) + (voff)[_i]), (PG8_LAS unsigned*)(lds + (bufoff) + ldsw + _i * 8192), 16, 0, 0); } while (0)
; #define PG8_LDA(dst, b, h) do { _Pragma("unroll") for (int m = 0; m < 4; ++m) _Pragma("unroll") for (int k = 0; k < 2; ++k) dst[m][k] = *(const PG8_LAS bf16x8*)(lds + PG8_SA(b, h) + aoff + m * 2048 + k * 1024); } while (0)
; #define PG8_LDB(dst, b, h) do { _Pragma("unroll") for (int n = 0; n < 2; ++n) _Pragma("unroll") for (int k = 0; k < 2; ++k) dst[n][k] = *(const PG8_LAS bf16x8*)(lds + PG8_SB(b, h) + boff + n * 2048 + k * 1024); } while (0)
; #define PG8_MMA(ai, bj, At, Bt) do { __builtin_amdgcn_s_setprio(1); _Pragma("unroll") for (int m = 0; m < 4; ++m) _Pragma("unroll") for (int n = 0; n < 2; ++n) _Pragma("unroll") for (int k = 0; k < 2; ++k) \
;         acc[ai][bj][m][n] = __builtin_amdgcn_mfma_f32_16x16x32_bf16(Bt[n][k], At[m][k], acc[ai][bj][m][n], 0, 0, 0); __builtin_amdgcn_s_setprio(0); } while (0)
; #define PG8_WAIT_V(n) asm volatile("s_waitcnt vmcnt(" #n ")" ::: "memory")
; #define PG8_WAIT_L(n) asm volatile("s_waitcnt lgkmcnt(" #n ")" ::: "memory")
; #define PG8_BAR __builtin_amdgcn_s_barrier()
; #define PG8_SCHED __builtin_amdgcn_sched_barrier(0)
; template <class Epi, class Sched, bool ALIGN_EPI = false, bool SP2 = false>
; __device__ __forceinline__ void gemm_phase(PG8_LAS unsigned char* lds, const Gemm g, const Sched& S, const Epi& E) {
;     ...
;             PG8_LDB(B0, 1, 0); PG8_LDB(B1, 1, 1); PG8_SCHED; PG8_LDA(At, 1, 0); PG8_STAGE(PG8_SA(0, 1), a2 + hstep, voffA);
;             PG8_WAIT_V(8); PG8_WAIT_L(0); PG8_BAR; PG8_MMA(0, 0, At, B0); PG8_MMA(0, 1, At, B1); PG8_BAR; PG8_SCHED;
;             PG8_LDA(At, 1, 1); PG8_STAGE(PG8_SB(1, 0), b3, voffB); PG8_STAGE(PG8_SB(1, 1), b3 + hstep, voffB); PG8_STAGE(PG8_SA(1, 0), a3, voffA);
;             PG8_WAIT_V(8); PG8_WAIT_L(0); PG8_BAR; PG8_MMA(1, 0, At, B0); PG8_MMA(1, 1, At, B1); PG8_BAR; PG8_SCHED;
	s_add_i32 s84, 0, 0x18000
	s_add_i32 s85, 0, 0x1c000
	v_add_u32_e32 v76, s84, v228
	v_add_u32_e32 v168, s85, v228
	ds_read_b128 v[64:67], v76
	ds_read_b128 v[68:71], v76 offset:1024
	ds_read_b128 v[72:75], v76 offset:2048
	ds_read_b128 v[76:79], v76 offset:3072
	ds_read_b128 v[156:159], v168
	ds_read_b128 v[160:163], v168 offset:1024
	ds_read_b128 v[164:167], v168 offset:2048
	ds_read_b128 v[168:171], v168 offset:3072
	s_add_u32 s64, s64, 0x40000
	s_addc_u32 s65, s65, 0
	s_mov_b32 m0, s20
	ds_read_b128 v[172:175], v230 offset:32768
	ds_read_b128 v[176:179], v230 offset:33792
	ds_read_b128 v[180:183], v230 offset:34816
	ds_read_b128 v[184:187], v230 offset:35840
	ds_read_b128 v[188:191], v230 offset:36864
	ds_read_b128 v[192:195], v230 offset:37888
	ds_read_b128 v[196:199], v230 offset:38912
	ds_read_b128 v[200:203], v230 offset:39936
	global_load_lds_dwordx4 v150, s[64:65]
	s_mov_b32 m0, s21
	s_nop 0
	global_load_lds_dwordx4 v148, s[64:65]
	s_waitcnt vmcnt(8)
	s_waitcnt lgkmcnt(0)
	s_barrier
	s_setprio 1
	s_waitcnt lgkmcnt(0)
	v_mfma_f32_16x16x32_bf16 v[142:145], v[64:67], v[172:175], v[142:145]
	v_mfma_f32_16x16x32_bf16 v[138:141], v[72:75], v[172:175], v[138:141]
	v_mfma_f32_16x16x32_bf16 v[134:137], v[64:67], v[180:183], v[134:137]
	v_mfma_f32_16x16x32_bf16 v[124:127], v[72:75], v[180:183], v[124:127]
	v_mfma_f32_16x16x32_bf16 v[108:111], v[64:67], v[188:191], v[108:111]
	v_mfma_f32_16x16x32_bf16 v[104:107], v[72:75], v[188:191], v[104:107]
	v_mfma_f32_16x16x32_bf16 v[100:103], v[64:67], v[196:199], v[100:103]
	v_mfma_f32_16x16x32_bf16 v[92:95], v[72:75], v[196:199], v[92:95]
	v_mfma_f32_16x16x32_bf16 v[142:145], v[68:71], v[176:179], v[142:145]
	v_mfma_f32_16x16x32_bf16 v[138:141], v[76:79], v[176:179], v[138:141]
	v_mfma_f32_16x16x32_bf16 v[134:137], v[68:71], v[184:187], v[134:137]
	v_mfma_f32_16x16x32_bf16 v[124:127], v[76:79], v[184:187], v[124:127]
	v_mfma_f32_16x16x32_bf16 v[108:111], v[68:71], v[192:195], v[108:111]
	v_mfma_f32_16x16x32_bf16 v[104:107], v[76:79], v[192:195], v[104:107]
	v_mfma_f32_16x16x32_bf16 v[100:103], v[68:71], v[200:203], v[100:103]
	v_mfma_f32_16x16x32_bf16 v[92:95], v[76:79], v[200:203], v[92:95]
	s_setprio 0
	s_setprio 1
	v_mfma_f32_16x16x32_bf16 v[130:133], v[156:159], v[172:175], v[130:133]
	v_mfma_f32_16x16x32_bf16 v[120:123], v[164:167], v[172:175], v[120:123]
	v_mfma_f32_16x16x32_bf16 v[116:119], v[156:159], v[180:183], v[116:119]
	v_mfma_f32_16x16x32_bf16 v[112:115], v[164:167], v[180:183], v[112:115]
	v_mfma_f32_16x16x32_bf16 v[96:99], v[156:159], v[188:191], v[96:99]
	v_mfma_f32_16x16x32_bf16 v[88:91], v[164:167], v[188:191], v[88:91]
	v_mfma_f32_16x16x32_bf16 v[84:87], v[156:159], v[196:199], v[84:87]
	v_mfma_f32_16x16x32_bf16 v[80:83], v[164:167], v[196:199], v[80:83]
	v_mfma_f32_16x16x32_bf16 v[130:133], v[160:163], v[176:179], v[130:133]
	v_mfma_f32_16x16x32_bf16 v[120:123], v[168:171], v[176:179], v[120:123]
	v_mfma_f32_16x16x32_bf16 v[116:119], v[160:163], v[184:187], v[116:119]
	v_mfma_f32_16x16x32_bf16 v[112:115], v[168:171], v[184:187], v[112:115]
	v_mfma_f32_16x16x32_bf16 v[96:99], v[160:163], v[192:195], v[96:99]
	v_mfma_f32_16x16x32_bf16 v[88:91], v[168:171], v[192:195], v[88:91]
	v_mfma_f32_16x16x32_bf16 v[84:87], v[160:163], v[200:203], v[84:87]
	v_mfma_f32_16x16x32_bf16 v[80:83], v[168:171], v[200:203], v[80:83]
	s_setprio 0
	s_barrier
	s_add_i32 s64, s84, s17
	s_add_i32 m0, s64, 0xffffff80
	ds_read_b128 v[172:175], v230 offset:49152
	ds_read_b128 v[176:179], v230 offset:50176
	ds_read_b128 v[180:183], v230 offset:51200
	ds_read_b128 v[184:187], v230 offset:52224
	ds_read_b128 v[188:191], v230 offset:53248
	ds_read_b128 v[192:195], v230 offset:54272
	ds_read_b128 v[196:199], v230 offset:55296
	ds_read_b128 v[200:203], v230 offset:56320
	global_load_lds_dwordx4 v128, s[58:59] offset:128
	s_add_i32 m0, s64, 0x1f80
	s_add_i32 s64, s85, s17
	global_load_lds_dwordx4 v146, s[58:59] offset:128
	s_add_u32 s58, s58, 0x40080
	s_addc_u32 s59, s59, 0
	s_mov_b32 m0, s64
	s_nop 0
	global_load_lds_dwordx4 v128, s[58:59]
	s_add_i32 m0, s64, 0x2000
	s_nop 0
	global_load_lds_dwordx4 v146, s[58:59]
	s_mov_b32 m0, s28
	s_nop 0
	global_load_lds_dwordx4 v150, s[100:101]
	s_mov_b32 m0, s29
	s_nop 0
	global_load_lds_dwordx4 v148, s[100:101]
	s_waitcnt vmcnt(8)
	s_waitcnt lgkmcnt(0)
	s_barrier
	s_setprio 1
	s_waitcnt lgkmcnt(0)
	v_mfma_f32_16x16x32_bf16 v[60:63], v[64:67], v[172:175], v[60:63]
	v_mfma_f32_16x16x32_bf16 v[56:59], v[72:75], v[172:175], v[56:59]
	v_mfma_f32_16x16x32_bf16 v[52:55], v[64:67], v[180:183], v[52:55]
	v_mfma_f32_16x16x32_bf16 v[44:47], v[72:75], v[180:183], v[44:47]
	v_mfma_f32_16x16x32_bf16 v[28:31], v[64:67], v[188:191], v[28:31]
	v_mfma_f32_16x16x32_bf16 v[24:27], v[72:75], v[188:191], v[24:27]
	v_mfma_f32_16x16x32_bf16 v[12:15], v[64:67], v[196:199], v[12:15]
	v_mfma_f32_16x16x32_bf16 v[8:11], v[72:75], v[196:199], v[8:11]
	v_mfma_f32_16x16x32_bf16 v[60:63], v[68:71], v[176:179], v[60:63]
	v_mfma_f32_16x16x32_bf16 v[56:59], v[76:79], v[176:179], v[56:59]
	v_mfma_f32_16x16x32_bf16 v[52:55], v[68:71], v[184:187], v[52:55]
	v_mfma_f32_16x16x32_bf16 v[44:47], v[76:79], v[184:187], v[44:47]
	v_mfma_f32_16x16x32_bf16 v[28:31], v[68:71], v[192:195], v[28:31]
	v_mfma_f32_16x16x32_bf16 v[24:27], v[76:79], v[192:195], v[24:27]
	v_mfma_f32_16x16x32_bf16 v[12:15], v[68:71], v[200:203], v[12:15]
	v_mfma_f32_16x16x32_bf16 v[8:11], v[76:79], v[200:203], v[8:11]
	s_setprio 0
	s_setprio 1
	v_mfma_f32_16x16x32_bf16 v[48:51], v[156:159], v[172:175], v[48:51]
	v_mfma_f32_16x16x32_bf16 v[40:43], v[164:167], v[172:175], v[40:43]
	v_mfma_f32_16x16x32_bf16 v[36:39], v[156:159], v[180:183], v[36:39]
	v_mfma_f32_16x16x32_bf16 v[32:35], v[164:167], v[180:183], v[32:35]
	v_mfma_f32_16x16x32_bf16 v[20:23], v[156:159], v[188:191], v[20:23]
	v_mfma_f32_16x16x32_bf16 v[16:19], v[164:167], v[188:191], v[16:19]
	v_mfma_f32_16x16x32_bf16 v[4:7], v[156:159], v[196:199], v[4:7]
	v_mfma_f32_16x16x32_bf16 v[0:3], v[164:167], v[196:199], v[0:3]
	v_mfma_f32_16x16x32_bf16 v[48:51], v[160:163], v[176:179], v[48:51]
	v_mfma_f32_16x16x32_bf16 v[40:43], v[168:171], v[176:179], v[40:43]
	v_mfma_f32_16x16x32_bf16 v[36:39], v[160:163], v[184:187], v[36:39]
	v_mfma_f32_16x16x32_bf16 v[32:35], v[168:171], v[184:187], v[32:35]
	v_mfma_f32_16x16x32_bf16 v[20:23], v[160:163], v[192:195], v[20:23]
	v_mfma_f32_16x16x32_bf16 v[16:19], v[168:171], v[192:195], v[16:19]
	v_mfma_f32_16x16x32_bf16 v[4:7], v[160:163], v[200:203], v[4:7]
	v_mfma_f32_16x16x32_bf16 v[0:3], v[168:171], v[200:203], v[0:3]
	s_setprio 0
	s_barrier
	s_add_i32 s94, s94, 2
	s_add_u32 vcc_lo, vcc_lo, 0x100
	s_addc_u32 vcc_hi, vcc_hi, 0
	s_add_u32 s88, s88, 0x100
	s_addc_u32 s93, s93, 0
	s_cmp_gt_u32 s94, 13
	s_cbranch_scc0 .LBB0_598
	s_and_b64 vcc, exec, s[72:73]
	s_cbranch_vccz .LBB0_601
	s_barrier

; #define PG8_STAGE(bufoff, gbase, voff) do { _Pragma("unroll") for (int _i = 0; _i < 2; ++_i) \
;         __builtin_amdgcn_global_load_lds((const unsigned*)((const char*)(gbase) + (voff)[_i]), (PG8_LAS unsigned*)(lds + (bufoff) + ldsw + _i * 8192), 16, 0, 0); } while (0)
; #define PG8_LDA(dst, b, h) do { _Pragma("unroll") for (int m = 0; m < 4; ++m) _Pragma("unroll") for (int k = 0; k < 2; ++k) dst[m][k] = *(const PG8_LAS bf16x8*)(lds + PG8_SA(b, h) + aoff + m * 2048 + k * 1024); } while (0)
; #define PG8_LDB(dst, b, h) do { _Pragma("unroll") for (int n = 0; n < 2; ++n) _Pragma("unroll") for (int k = 0; k < 2; ++k) dst[n][k] = *(const PG8_LAS bf16x8*)(lds + PG8_SB(b, h) + boff + n * 2048 + k * 1024); } while (0)
; #define PG8_MMA(ai, bj, At, Bt) do { __builtin_amdgcn_s_setprio(1); _Pragma("unroll") for (int m = 0; m < 4; ++m) _Pragma("unroll") for (int n = 0; n < 2; ++n) _Pragma("unroll") for (int k = 0; k < 2; ++k) \
;         acc[ai][bj][m][n] = __builtin_amdgcn_mfma_f32_16x16x32_bf16(Bt[n][k], At[m][k], acc[ai][bj][m][n], 0, 0, 0); __builtin_amdgcn_s_setprio(0); } while (0)
; #define PG8_WAIT_V(n) asm volatile("s_waitcnt vmcnt(" #n ")" ::: "memory")
; #define PG8_BAR __builtin_amdgcn_s_barrier()
; template <class Epi, class Sched, bool ALIGN_EPI = false, bool SP2 = false>
; __device__ __forceinline__ void gemm_phase(PG8_LAS unsigned char* lds, const Gemm g, const Sched& S, const Epi& E) {
;     ...
;         for (int t = 0; t < nt; t += 2) {
;             const bool last = (t == nt - 2);
;             const char* a1 = cA + (size_t)(t + 1) * kstep;
;             const char* a2 = last ? nA : cA + (size_t)(t + 2) * kstep; const char* b2 = last ? nB : cB + (size_t)(t + 2) * kstep;
;             const char* a3 = a2 + kstep; const char* b3 = b2 + kstep;
;             if (last && has_next) S.a_ready(nxt);
;             if constexpr (SP2) {
;             PG8_LDB(B0, 0, 0); PG8_LDB(B1, 0, 1); PG8_SCHED; PG8_LDA(At, 0, 0); PG8_STAGE(PG8_SA(1, 1), a1 + hstep, voffA);
;             PG8_WAIT_V(8); PG8_WAIT_L(0); PG8_BAR; PG8_MMA(0, 0, At, B0); PG8_MMA(0, 1, At, B1); PG8_BAR; PG8_SCHED;
;             PG8_LDA(At, 0, 1); PG8_STAGE(PG8_SB(0, 0), b2, voffB); PG8_STAGE(PG8_SB(0, 1), b2 + hstep, voffB); PG8_STAGE(PG8_SA(0, 0), a2, voffA);
;             PG8_WAIT_V(8); PG8_WAIT_L(0); PG8_BAR; PG8_MMA(1, 0, At, B0); PG8_MMA(1, 1, At, B1); PG8_BAR; PG8_SCHED;
.LBB0_813:
	s_add_u32 s8, s66, 0xfffc0080
	s_addc_u32 s37, s67, -1
	s_add_i32 s49, 0, 0x10000
	s_cmp_eq_u32 s36, 12
	s_cselect_b32 s65, s28, s37
	s_cselect_b32 s64, s29, s8
	s_cselect_b32 s59, s30, s35
	s_cselect_b32 s58, s31, s34
	s_add_i32 s8, 0, 0x14000
	v_add_u32_e32 v156, s49, v145
	v_add_u32_e32 v172, s8, v145
	ds_read_b128 v[140:143], v156
	ds_read_b128 v[148:151], v156 offset:1024
	ds_read_b128 v[152:155], v156 offset:2048
	ds_read_b128 v[156:159], v156 offset:3072
	ds_read_b128 v[160:163], v172
	ds_read_b128 v[164:167], v172 offset:1024
	ds_read_b128 v[168:171], v172 offset:2048
	ds_read_b128 v[172:175], v172 offset:3072
	s_add_i32 m0, s18, 0xc000
	ds_read_b128 v[176:179], v147
	ds_read_b128 v[180:183], v147 offset:1024
	ds_read_b128 v[184:187], v147 offset:2048
	ds_read_b128 v[188:191], v147 offset:3072
	ds_read_b128 v[192:195], v147 offset:4096
	ds_read_b128 v[196:199], v147 offset:5120
	ds_read_b128 v[200:203], v147 offset:6144
	ds_read_b128 v[204:207], v147 offset:7168
	global_load_lds_dwordx4 v136, s[66:67]
	s_add_i32 m0, s18, 0xe000
	s_nop 0
	global_load_lds_dwordx4 v138, s[66:67]
	s_waitcnt vmcnt(8)
	s_waitcnt lgkmcnt(0)
	s_barrier
	s_setprio 1
	s_waitcnt lgkmcnt(0)
	v_mfma_f32_16x16x32_bf16 v[124:127], v[140:143], v[176:179], v[124:127]
	v_mfma_f32_16x16x32_bf16 v[116:119], v[152:155], v[176:179], v[116:119]
	v_mfma_f32_16x16x32_bf16 v[108:111], v[140:143], v[184:187], v[108:111]
	v_mfma_f32_16x16x32_bf16 v[100:103], v[152:155], v[184:187], v[100:103]
	v_mfma_f32_16x16x32_bf16 v[92:95], v[140:143], v[192:195], v[92:95]
	v_mfma_f32_16x16x32_bf16 v[84:87], v[152:155], v[192:195], v[84:87]
	v_mfma_f32_16x16x32_bf16 v[76:79], v[140:143], v[200:203], v[76:79]
	v_mfma_f32_16x16x32_bf16 v[68:71], v[152:155], v[200:203], v[68:71]
	v_mfma_f32_16x16x32_bf16 v[124:127], v[148:151], v[180:183], v[124:127]
	v_mfma_f32_16x16x32_bf16 v[116:119], v[156:159], v[180:183], v[116:119]
	v_mfma_f32_16x16x32_bf16 v[108:111], v[148:151], v[188:191], v[108:111]
	v_mfma_f32_16x16x32_bf16 v[100:103], v[156:159], v[188:191], v[100:103]
	v_mfma_f32_16x16x32_bf16 v[92:95], v[148:151], v[196:199], v[92:95]
	v_mfma_f32_16x16x32_bf16 v[84:87], v[156:159], v[196:199], v[84:87]
	v_mfma_f32_16x16x32_bf16 v[76:79], v[148:151], v[204:207], v[76:79]
	v_mfma_f32_16x16x32_bf16 v[68:71], v[156:159], v[204:207], v[68:71]
	s_setprio 0
	s_setprio 1
	v_mfma_f32_16x16x32_bf16 v[120:123], v[160:163], v[176:179], v[120:123]
	v_mfma_f32_16x16x32_bf16 v[112:115], v[168:171], v[176:179], v[112:115]
	v_mfma_f32_16x16x32_bf16 v[104:107], v[160:163], v[184:187], v[104:107]
	v_mfma_f32_16x16x32_bf16 v[96:99], v[168:171], v[184:187], v[96:99]
	v_mfma_f32_16x16x32_bf16 v[88:91], v[160:163], v[192:195], v[88:91]
	v_mfma_f32_16x16x32_bf16 v[80:83], v[168:171], v[192:195], v[80:83]
	v_mfma_f32_16x16x32_bf16 v[72:75], v[160:163], v[200:203], v[72:75]
	v_mfma_f32_16x16x32_bf16 v[64:67], v[168:171], v[200:203], v[64:67]
	v_mfma_f32_16x16x32_bf16 v[120:123], v[164:167], v[180:183], v[120:123]
	v_mfma_f32_16x16x32_bf16 v[112:115], v[172:175], v[180:183], v[112:115]
	v_mfma_f32_16x16x32_bf16 v[104:107], v[164:167], v[188:191], v[104:107]
	v_mfma_f32_16x16x32_bf16 v[96:99], v[172:175], v[188:191], v[96:99]
	v_mfma_f32_16x16x32_bf16 v[88:91], v[164:167], v[196:199], v[88:91]
	v_mfma_f32_16x16x32_bf16 v[80:83], v[172:175], v[196:199], v[80:83]
	v_mfma_f32_16x16x32_bf16 v[72:75], v[164:167], v[204:207], v[72:75]
	v_mfma_f32_16x16x32_bf16 v[64:67], v[172:175], v[204:207], v[64:67]
	s_setprio 0
	s_barrier
	s_add_i32 s37, s49, s17
	s_mov_b32 m0, s37
	ds_read_b128 v[176:179], v147 offset:16384
	ds_read_b128 v[180:183], v147 offset:17408
	ds_read_b128 v[184:187], v147 offset:18432
	ds_read_b128 v[188:191], v147 offset:19456
	ds_read_b128 v[192:195], v147 offset:20480
	ds_read_b128 v[196:199], v147 offset:21504
	ds_read_b128 v[200:203], v147 offset:22528
	ds_read_b128 v[204:207], v147 offset:23552
	global_load_lds_dwordx4 v128, s[58:59]
	s_add_i32 m0, s37, 0x2000
	s_add_u32 s72, s58, 0x40000
	s_addc_u32 s73, s59, 0
	s_add_i32 s8, s8, s17
	global_load_lds_dwordx4 v130, s[58:59]
	s_mov_b32 m0, s8
	s_nop 0
	global_load_lds_dwordx4 v128, s[72:73]
	s_add_i32 m0, s8, 0x2000
	s_nop 0
	global_load_lds_dwordx4 v130, s[72:73]
	s_mov_b32 m0, s18
	s_nop 0
	global_load_lds_dwordx4 v134, s[64:65]
	s_mov_b32 m0, s19
	s_nop 0
	global_load_lds_dwordx4 v132, s[64:65]
	s_add_u32 s100, s64, 0x80
	s_addc_u32 s101, s65, 0
	s_waitcnt vmcnt(8)
	s_waitcnt lgkmcnt(0)
	s_barrier
	s_setprio 1
	s_waitcnt lgkmcnt(0)
	v_mfma_f32_16x16x32_bf16 v[60:63], v[140:143], v[176:179], v[60:63]
	v_mfma_f32_16x16x32_bf16 v[52:55], v[152:155], v[176:179], v[52:55]
	v_mfma_f32_16x16x32_bf16 v[44:47], v[140:143], v[184:187], v[44:47]
	v_mfma_f32_16x16x32_bf16 v[36:39], v[152:155], v[184:187], v[36:39]
	v_mfma_f32_16x16x32_bf16 v[28:31], v[140:143], v[192:195], v[28:31]
	v_mfma_f32_16x16x32_bf16 v[20:23], v[152:155], v[192:195], v[20:23]
	v_mfma_f32_16x16x32_bf16 v[12:15], v[140:143], v[200:203], v[12:15]
	v_mfma_f32_16x16x32_bf16 v[4:7], v[152:155], v[200:203], v[4:7]
	v_mfma_f32_16x16x32_bf16 v[60:63], v[148:151], v[180:183], v[60:63]
	v_mfma_f32_16x16x32_bf16 v[52:55], v[156:159], v[180:183], v[52:55]
	v_mfma_f32_16x16x32_bf16 v[44:47], v[148:151], v[188:191], v[44:47]
	v_mfma_f32_16x16x32_bf16 v[36:39], v[156:159], v[188:191], v[36:39]
	v_mfma_f32_16x16x32_bf16 v[28:31], v[148:151], v[196:199], v[28:31]
	v_mfma_f32_16x16x32_bf16 v[20:23], v[156:159], v[196:199], v[20:23]
	v_mfma_f32_16x16x32_bf16 v[12:15], v[148:151], v[204:207], v[12:15]
	v_mfma_f32_16x16x32_bf16 v[4:7], v[156:159], v[204:207], v[4:7]
	s_setprio 0
	s_setprio 1
	v_mfma_f32_16x16x32_bf16 v[56:59], v[160:163], v[176:179], v[56:59]
	v_mfma_f32_16x16x32_bf16 v[48:51], v[168:171], v[176:179], v[48:51]
	v_mfma_f32_16x16x32_bf16 v[40:43], v[160:163], v[184:187], v[40:43]
	v_mfma_f32_16x16x32_bf16 v[32:35], v[168:171], v[184:187], v[32:35]
	v_mfma_f32_16x16x32_bf16 v[24:27], v[160:163], v[192:195], v[24:27]
	v_mfma_f32_16x16x32_bf16 v[16:19], v[168:171], v[192:195], v[16:19]
	v_mfma_f32_16x16x32_bf16 v[8:11], v[160:163], v[200:203], v[8:11]
	v_mfma_f32_16x16x32_bf16 v[0:3], v[168:171], v[200:203], v[0:3]
	v_mfma_f32_16x16x32_bf16 v[56:59], v[164:167], v[180:183], v[56:59]
	v_mfma_f32_16x16x32_bf16 v[48:51], v[172:175], v[180:183], v[48:51]
	v_mfma_f32_16x16x32_bf16 v[40:43], v[164:167], v[188:191], v[40:43]
	v_mfma_f32_16x16x32_bf16 v[32:35], v[172:175], v[188:191], v[32:35]
	v_mfma_f32_16x16x32_bf16 v[24:27], v[164:167], v[196:199], v[24:27]
	v_mfma_f32_16x16x32_bf16 v[16:19], v[172:175], v[196:199], v[16:19]
	v_mfma_f32_16x16x32_bf16 v[8:11], v[164:167], v[204:207], v[8:11]
	v_mfma_f32_16x16x32_bf16 v[0:3], v[172:175], v[204:207], v[0:3]
	s_setprio 0
	s_barrier
; #define PG8_STAGE(bufoff, gbase, voff) do { _Pragma("unroll") for (int _i = 0; _i < 2; ++_i) \
;         __builtin_amdgcn_global_load_lds((const unsigned*)((const char*)(gbase) + (voff)[_i]), (PG8_LAS unsigned*)(lds + (bufoff) + ldsw + _i * 8192), 16, 0, 0); } while (0)
; #define PG8_LDA(dst, b, h) do { _Pragma("unroll") for (int m = 0; m < 4; ++m) _Pragma("unroll") for (int k = 0; k < 2; ++k) dst[m][k] = *(const PG8_LAS bf16x8*)(lds + PG8_SA(b, h) + aoff + m * 2048 + k * 1024); } while (0)
; #define PG8_LDB(dst, b, h) do { _Pragma("unroll") for (int n = 0; n < 2; ++n) _Pragma("unroll") for (int k = 0; k < 2; ++k) dst[n][k] = *(const PG8_LAS bf16x8*)(lds + PG8_SB(b, h) + boff + n * 2048 + k * 1024); } while (0)
; #define PG8_MMA(ai, bj, At, Bt) do { __builtin_amdgcn_s_setprio(1); _Pragma("unroll") for (int m = 0; m < 4; ++m) _Pragma("unroll") for (int n = 0; n < 2; ++n) _Pragma("unroll") for (int k = 0; k < 2; ++k) \
;         acc[ai][bj][m][n] = __builtin_amdgcn_mfma_f32_16x16x32_bf16(Bt[n][k], At[m][k], acc[ai][bj][m][n], 0, 0, 0); __builtin_amdgcn_s_setprio(0); } while (0)
; #define PG8_WAIT_V(n) asm volatile("s_waitcnt vmcnt(" #n ")" ::: "memory")
; #define PG8_WAIT_L(n) asm volatile("s_waitcnt lgkmcnt(" #n ")" ::: "memory")
; #define PG8_BAR __builtin_amdgcn_s_barrier()
; #define PG8_SCHED __builtin_amdgcn_sched_barrier(0)
; template <class Epi, class Sched, bool ALIGN_EPI = false, bool SP2 = false>
; __device__ __forceinline__ void gemm_phase(PG8_LAS unsigned char* lds, const Gemm g, const Sched& S, const Epi& E) {
;     ...
;             PG8_LDB(B0, 1, 0); PG8_LDB(B1, 1, 1); PG8_SCHED; PG8_LDA(At, 1, 0); PG8_STAGE(PG8_SA(0, 1), a2 + hstep, voffA);
;             PG8_WAIT_V(8); PG8_WAIT_L(0); PG8_BAR; PG8_MMA(0, 0, At, B0); PG8_MMA(0, 1, At, B1); PG8_BAR; PG8_SCHED;
;             PG8_LDA(At, 1, 1); PG8_STAGE(PG8_SB(1, 0), b3, voffB); PG8_STAGE(PG8_SB(1, 1), b3 + hstep, voffB); PG8_STAGE(PG8_SA(1, 0), a3, voffA);
;             PG8_WAIT_V(8); PG8_WAIT_L(0); PG8_BAR; PG8_MMA(1, 0, At, B0); PG8_MMA(1, 1, At, B1); PG8_BAR; PG8_SCHED;
	s_add_i32 s8, 0, 0x18000
	s_add_i32 s37, 0, 0x1c000
	v_add_u32_e32 v156, s8, v145
	v_add_u32_e32 v172, s37, v145
	ds_read_b128 v[140:143], v156
	ds_read_b128 v[148:151], v156 offset:1024
	ds_read_b128 v[152:155], v156 offset:2048
	ds_read_b128 v[156:159], v156 offset:3072
	ds_read_b128 v[160:163], v172
	ds_read_b128 v[164:167], v172 offset:1024
	ds_read_b128 v[168:171], v172 offset:2048
	ds_read_b128 v[172:175], v172 offset:3072
	s_add_u32 s64, s64, 0x40000
	s_addc_u32 s65, s65, 0
	s_mov_b32 m0, s20
	ds_read_b128 v[176:179], v147 offset:32768
	ds_read_b128 v[180:183], v147 offset:33792
	ds_read_b128 v[184:187], v147 offset:34816
	ds_read_b128 v[188:191], v147 offset:35840
	ds_read_b128 v[192:195], v147 offset:36864
	ds_read_b128 v[196:199], v147 offset:37888
	ds_read_b128 v[200:203], v147 offset:38912
	ds_read_b128 v[204:207], v147 offset:39936
	global_load_lds_dwordx4 v134, s[64:65]
	s_mov_b32 m0, s21
	s_nop 0
	global_load_lds_dwordx4 v132, s[64:65]
	s_waitcnt vmcnt(8)
	s_waitcnt lgkmcnt(0)
	s_barrier
	s_setprio 1
	s_waitcnt lgkmcnt(0)
	v_mfma_f32_16x16x32_bf16 v[124:127], v[140:143], v[176:179], v[124:127]
	v_mfma_f32_16x16x32_bf16 v[116:119], v[152:155], v[176:179], v[116:119]
	v_mfma_f32_16x16x32_bf16 v[108:111], v[140:143], v[184:187], v[108:111]
	v_mfma_f32_16x16x32_bf16 v[100:103], v[152:155], v[184:187], v[100:103]
	v_mfma_f32_16x16x32_bf16 v[92:95], v[140:143], v[192:195], v[92:95]
	v_mfma_f32_16x16x32_bf16 v[84:87], v[152:155], v[192:195], v[84:87]
	v_mfma_f32_16x16x32_bf16 v[76:79], v[140:143], v[200:203], v[76:79]
	v_mfma_f32_16x16x32_bf16 v[68:71], v[152:155], v[200:203], v[68:71]
	v_mfma_f32_16x16x32_bf16 v[124:127], v[148:151], v[180:183], v[124:127]
	v_mfma_f32_16x16x32_bf16 v[116:119], v[156:159], v[180:183], v[116:119]
	v_mfma_f32_16x16x32_bf16 v[108:111], v[148:151], v[188:191], v[108:111]
	v_mfma_f32_16x16x32_bf16 v[100:103], v[156:159], v[188:191], v[100:103]
	v_mfma_f32_16x16x32_bf16 v[92:95], v[148:151], v[196:199], v[92:95]
	v_mfma_f32_16x16x32_bf16 v[84:87], v[156:159], v[196:199], v[84:87]
	v_mfma_f32_16x16x32_bf16 v[76:79], v[148:151], v[204:207], v[76:79]
	v_mfma_f32_16x16x32_bf16 v[68:71], v[156:159], v[204:207], v[68:71]
	s_setprio 0
	s_setprio 1
	v_mfma_f32_16x16x32_bf16 v[120:123], v[160:163], v[176:179], v[120:123]
	v_mfma_f32_16x16x32_bf16 v[112:115], v[168:171], v[176:179], v[112:115]
	v_mfma_f32_16x16x32_bf16 v[104:107], v[160:163], v[184:187], v[104:107]
	v_mfma_f32_16x16x32_bf16 v[96:99], v[168:171], v[184:187], v[96:99]
	v_mfma_f32_16x16x32_bf16 v[88:91], v[160:163], v[192:195], v[88:91]
	v_mfma_f32_16x16x32_bf16 v[80:83], v[168:171], v[192:195], v[80:83]
	v_mfma_f32_16x16x32_bf16 v[72:75], v[160:163], v[200:203], v[72:75]
	v_mfma_f32_16x16x32_bf16 v[64:67], v[168:171], v[200:203], v[64:67]
	v_mfma_f32_16x16x32_bf16 v[120:123], v[164:167], v[180:183], v[120:123]
	v_mfma_f32_16x16x32_bf16 v[112:115], v[172:175], v[180:183], v[112:115]
	v_mfma_f32_16x16x32_bf16 v[104:107], v[164:167], v[188:191], v[104:107]
	v_mfma_f32_16x16x32_bf16 v[96:99], v[172:175], v[188:191], v[96:99]
	v_mfma_f32_16x16x32_bf16 v[88:91], v[164:167], v[196:199], v[88:91]
	v_mfma_f32_16x16x32_bf16 v[80:83], v[172:175], v[196:199], v[80:83]
	v_mfma_f32_16x16x32_bf16 v[72:75], v[164:167], v[204:207], v[72:75]
	v_mfma_f32_16x16x32_bf16 v[64:67], v[172:175], v[204:207], v[64:67]
	s_setprio 0
	s_barrier
	s_add_i32 s8, s8, s17
	s_add_i32 m0, s8, 0xffffff80
	ds_read_b128 v[176:179], v147 offset:49152
	ds_read_b128 v[180:183], v147 offset:50176
	ds_read_b128 v[184:187], v147 offset:51200
	ds_read_b128 v[188:191], v147 offset:52224
	ds_read_b128 v[192:195], v147 offset:53248
	ds_read_b128 v[196:199], v147 offset:54272
	ds_read_b128 v[200:203], v147 offset:55296
	ds_read_b128 v[204:207], v147 offset:56320
	global_load_lds_dwordx4 v128, s[58:59] offset:128
	s_add_i32 m0, s8, 0x1f80
	s_add_i32 s8, s37, s17
	global_load_lds_dwordx4 v130, s[58:59] offset:128
	s_add_u32 s58, s58, 0x40080
	s_addc_u32 s59, s59, 0
	s_mov_b32 m0, s8
	s_nop 0
	global_load_lds_dwordx4 v128, s[58:59]
	s_add_i32 m0, s8, 0x2000
	s_nop 0
	global_load_lds_dwordx4 v130, s[58:59]
	s_mov_b32 m0, s22
	s_nop 0
	global_load_lds_dwordx4 v134, s[100:101]
	s_mov_b32 m0, s23
	s_nop 0
	global_load_lds_dwordx4 v132, s[100:101]
	s_waitcnt vmcnt(8)
	s_waitcnt lgkmcnt(0)
	s_barrier
	s_setprio 1
	s_waitcnt lgkmcnt(0)
	v_mfma_f32_16x16x32_bf16 v[60:63], v[140:143], v[176:179], v[60:63]
	v_mfma_f32_16x16x32_bf16 v[52:55], v[152:155], v[176:179], v[52:55]
	v_mfma_f32_16x16x32_bf16 v[44:47], v[140:143], v[184:187], v[44:47]
	v_mfma_f32_16x16x32_bf16 v[36:39], v[152:155], v[184:187], v[36:39]
	v_mfma_f32_16x16x32_bf16 v[28:31], v[140:143], v[192:195], v[28:31]
	v_mfma_f32_16x16x32_bf16 v[20:23], v[152:155], v[192:195], v[20:23]
	v_mfma_f32_16x16x32_bf16 v[12:15], v[140:143], v[200:203], v[12:15]
	v_mfma_f32_16x16x32_bf16 v[4:7], v[152:155], v[200:203], v[4:7]
	v_mfma_f32_16x16x32_bf16 v[60:63], v[148:151], v[180:183], v[60:63]
	v_mfma_f32_16x16x32_bf16 v[52:55], v[156:159], v[180:183], v[52:55]
	v_mfma_f32_16x16x32_bf16 v[44:47], v[148:151], v[188:191], v[44:47]
	v_mfma_f32_16x16x32_bf16 v[36:39], v[156:159], v[188:191], v[36:39]
	v_mfma_f32_16x16x32_bf16 v[28:31], v[148:151], v[196:199], v[28:31]
	v_mfma_f32_16x16x32_bf16 v[20:23], v[156:159], v[196:199], v[20:23]
	v_mfma_f32_16x16x32_bf16 v[12:15], v[148:151], v[204:207], v[12:15]
	v_mfma_f32_16x16x32_bf16 v[4:7], v[156:159], v[204:207], v[4:7]
	s_setprio 0
	s_setprio 1
	v_mfma_f32_16x16x32_bf16 v[56:59], v[160:163], v[176:179], v[56:59]
	v_mfma_f32_16x16x32_bf16 v[48:51], v[168:171], v[176:179], v[48:51]
	v_mfma_f32_16x16x32_bf16 v[40:43], v[160:163], v[184:187], v[40:43]
	v_mfma_f32_16x16x32_bf16 v[32:35], v[168:171], v[184:187], v[32:35]
	v_mfma_f32_16x16x32_bf16 v[24:27], v[160:163], v[192:195], v[24:27]
	v_mfma_f32_16x16x32_bf16 v[16:19], v[168:171], v[192:195], v[16:19]
	v_mfma_f32_16x16x32_bf16 v[8:11], v[160:163], v[200:203], v[8:11]
	v_mfma_f32_16x16x32_bf16 v[0:3], v[168:171], v[200:203], v[0:3]
	v_mfma_f32_16x16x32_bf16 v[56:59], v[164:167], v[180:183], v[56:59]
	v_mfma_f32_16x16x32_bf16 v[48:51], v[172:175], v[180:183], v[48:51]
	v_mfma_f32_16x16x32_bf16 v[40:43], v[164:167], v[188:191], v[40:43]
	v_mfma_f32_16x16x32_bf16 v[32:35], v[172:175], v[188:191], v[32:35]
	v_mfma_f32_16x16x32_bf16 v[24:27], v[164:167], v[196:199], v[24:27]
	v_mfma_f32_16x16x32_bf16 v[16:19], v[172:175], v[196:199], v[16:19]
	v_mfma_f32_16x16x32_bf16 v[8:11], v[164:167], v[204:207], v[8:11]
	v_mfma_f32_16x16x32_bf16 v[0:3], v[172:175], v[204:207], v[0:3]
	s_setprio 0
	s_barrier
	s_add_i32 s36, s36, 2
	s_add_u32 s66, s66, 0x100
	s_addc_u32 s67, s67, 0
	s_add_u32 s34, s34, 0x100
	s_addc_u32 s35, s35, 0
	s_cmp_gt_u32 s36, 13
	s_cbranch_scc0 .LBB0_813
	s_and_b64 vcc, exec, s[46:47]
	s_cbranch_vccz .LBB0_816
	s_barrier

; #define PG8_STAGE(bufoff, gbase, voff) do { _Pragma("unroll") for (int _i = 0; _i < 2; ++_i) \
;         __builtin_amdgcn_global_load_lds((const unsigned*)((const char*)(gbase) + (voff)[_i]), (PG8_LAS unsigned*)(lds + (bufoff) + ldsw + _i * 8192), 16, 0, 0); } while (0)
; #define PG8_LDA(dst, b, h) do { _Pragma("unroll") for (int m = 0; m < 4; ++m) _Pragma("unroll") for (int k = 0; k < 2; ++k) dst[m][k] = *(const PG8_LAS bf16x8*)(lds + PG8_SA(b, h) + aoff + m * 2048 + k * 1024); } while (0)
; #define PG8_LDB(dst, b, h) do { _Pragma("unroll") for (int n = 0; n < 2; ++n) _Pragma("unroll") for (int k = 0; k < 2; ++k) dst[n][k] = *(const PG8_LAS bf16x8*)(lds + PG8_SB(b, h) + boff + n * 2048 + k * 1024); } while (0)
; #define PG8_MMA(ai, bj, At, Bt) do { __builtin_amdgcn_s_setprio(1); _Pragma("unroll") for (int m = 0; m < 4; ++m) _Pragma("unroll") for (int n = 0; n < 2; ++n) _Pragma("unroll") for (int k = 0; k < 2; ++k) \
;         acc[ai][bj][m][n] = __builtin_amdgcn_mfma_f32_16x16x32_bf16(Bt[n][k], At[m][k], acc[ai][bj][m][n], 0, 0, 0); __builtin_amdgcn_s_setprio(0); } while (0)
; #define PG8_WAIT_V(n) asm volatile("s_waitcnt vmcnt(" #n ")" ::: "memory")
; #define PG8_BAR __builtin_amdgcn_s_barrier()
; template <class Epi, class Sched, bool ALIGN_EPI = false, bool SP2 = false>
; __device__ __forceinline__ void gemm_phase(PG8_LAS unsigned char* lds, const Gemm g, const Sched& S, const Epi& E) {
;     ...
;         for (int t = 0; t < nt; t += 2) {
;             const bool last = (t == nt - 2);
;             const char* a1 = cA + (size_t)(t + 1) * kstep;
;             const char* a2 = last ? nA : cA + (size_t)(t + 2) * kstep; const char* b2 = last ? nB : cB + (size_t)(t + 2) * kstep;
;             const char* a3 = a2 + kstep; const char* b3 = b2 + kstep;
;             if (last && has_next) S.a_ready(nxt);
;             if constexpr (SP2) {
;             PG8_LDB(B0, 0, 0); PG8_LDB(B1, 0, 1); PG8_SCHED; PG8_LDA(At, 0, 0); PG8_STAGE(PG8_SA(1, 1), a1 + hstep, voffA);
;             PG8_WAIT_V(8); PG8_WAIT_L(0); PG8_BAR; PG8_MMA(0, 0, At, B0); PG8_MMA(0, 1, At, B1); PG8_BAR; PG8_SCHED;
;             PG8_LDA(At, 0, 1); PG8_STAGE(PG8_SB(0, 0), b2, voffB); PG8_STAGE(PG8_SB(0, 1), b2 + hstep, voffB); PG8_STAGE(PG8_SA(0, 0), a2, voffA);
;             PG8_WAIT_V(8); PG8_WAIT_L(0); PG8_BAR; PG8_MMA(1, 0, At, B0); PG8_MMA(1, 1, At, B1); PG8_BAR; PG8_SCHED;
.LBB0_957:
	s_add_u32 s44, s96, 0x100
	s_addc_u32 s45, s97, 0
	s_add_i32 s8, 0, 0x10000
	s_cmp_eq_u32 s70, 40
	s_cselect_b32 s65, s67, s45
	s_cselect_b32 s64, s66, s44
	s_cselect_b32 s47, s73, s37
	s_cselect_b32 s46, s72, s36
	s_add_i32 s88, 0, 0x14000
	v_add_u32_e32 v142, s8, v185
	v_add_u32_e32 v168, s88, v185
	ds_read_b128 v[130:133], v142
	ds_read_b128 v[134:137], v142 offset:1024
	ds_read_b128 v[138:141], v142 offset:2048
	ds_read_b128 v[142:145], v142 offset:3072
	ds_read_b128 v[156:159], v168
	ds_read_b128 v[160:163], v168 offset:1024
	ds_read_b128 v[164:167], v168 offset:2048
	ds_read_b128 v[168:171], v168 offset:3072
	s_add_i32 m0, s15, 0xc000
	ds_read_b128 v[172:175], v191
	ds_read_b128 v[176:179], v191 offset:1024
	ds_read_b128 v[180:183], v191 offset:2048
	ds_read_b128 v[186:189], v191 offset:3072
	ds_read_b128 v[192:195], v191 offset:4096
	ds_read_b128 v[196:199], v191 offset:5120
	ds_read_b128 v[200:203], v191 offset:6144
	ds_read_b128 v[204:207], v191 offset:7168
	global_load_lds_dwordx4 v152, s[96:97]
	s_add_i32 m0, s15, 0xe000
	s_nop 0
	global_load_lds_dwordx4 v154, s[96:97]
	s_waitcnt vmcnt(8)
	s_waitcnt lgkmcnt(0)
	s_barrier
	s_setprio 1
	s_waitcnt lgkmcnt(0)
	v_mfma_f32_16x16x32_bf16 v[124:127], v[130:133], v[172:175], v[124:127]
	v_mfma_f32_16x16x32_bf16 v[120:123], v[138:141], v[172:175], v[120:123]
	v_mfma_f32_16x16x32_bf16 v[108:111], v[130:133], v[180:183], v[108:111]
	v_mfma_f32_16x16x32_bf16 v[104:107], v[138:141], v[180:183], v[104:107]
	v_mfma_f32_16x16x32_bf16 v[92:95], v[130:133], v[192:195], v[92:95]
	v_mfma_f32_16x16x32_bf16 v[88:91], v[138:141], v[192:195], v[88:91]
	v_mfma_f32_16x16x32_bf16 v[76:79], v[130:133], v[200:203], v[76:79]
	v_mfma_f32_16x16x32_bf16 v[72:75], v[138:141], v[200:203], v[72:75]
	v_mfma_f32_16x16x32_bf16 v[124:127], v[134:137], v[176:179], v[124:127]
	v_mfma_f32_16x16x32_bf16 v[120:123], v[142:145], v[176:179], v[120:123]
	v_mfma_f32_16x16x32_bf16 v[108:111], v[134:137], v[186:189], v[108:111]
	v_mfma_f32_16x16x32_bf16 v[104:107], v[142:145], v[186:189], v[104:107]
	v_mfma_f32_16x16x32_bf16 v[92:95], v[134:137], v[196:199], v[92:95]
	v_mfma_f32_16x16x32_bf16 v[88:91], v[142:145], v[196:199], v[88:91]
	v_mfma_f32_16x16x32_bf16 v[76:79], v[134:137], v[204:207], v[76:79]
	v_mfma_f32_16x16x32_bf16 v[72:75], v[142:145], v[204:207], v[72:75]
	s_setprio 0
	s_setprio 1
	v_mfma_f32_16x16x32_bf16 v[116:119], v[156:159], v[172:175], v[116:119]
	v_mfma_f32_16x16x32_bf16 v[112:115], v[164:167], v[172:175], v[112:115]
	v_mfma_f32_16x16x32_bf16 v[100:103], v[156:159], v[180:183], v[100:103]
	v_mfma_f32_16x16x32_bf16 v[96:99], v[164:167], v[180:183], v[96:99]
	v_mfma_f32_16x16x32_bf16 v[84:87], v[156:159], v[192:195], v[84:87]
	v_mfma_f32_16x16x32_bf16 v[80:83], v[164:167], v[192:195], v[80:83]
	v_mfma_f32_16x16x32_bf16 v[68:71], v[156:159], v[200:203], v[68:71]
	v_mfma_f32_16x16x32_bf16 v[64:67], v[164:167], v[200:203], v[64:67]
	v_mfma_f32_16x16x32_bf16 v[116:119], v[160:163], v[176:179], v[116:119]
	v_mfma_f32_16x16x32_bf16 v[112:115], v[168:171], v[176:179], v[112:115]
	v_mfma_f32_16x16x32_bf16 v[100:103], v[160:163], v[186:189], v[100:103]
	v_mfma_f32_16x16x32_bf16 v[96:99], v[168:171], v[186:189], v[96:99]
	v_mfma_f32_16x16x32_bf16 v[84:87], v[160:163], v[196:199], v[84:87]
	v_mfma_f32_16x16x32_bf16 v[80:83], v[168:171], v[196:199], v[80:83]
	v_mfma_f32_16x16x32_bf16 v[68:71], v[160:163], v[204:207], v[68:71]
	v_mfma_f32_16x16x32_bf16 v[64:67], v[168:171], v[204:207], v[64:67]
	s_setprio 0
	s_barrier
	s_add_i32 s8, s8, s14
	s_mov_b32 m0, s8
	ds_read_b128 v[172:175], v191 offset:16384
	ds_read_b128 v[176:179], v191 offset:17408
	ds_read_b128 v[180:183], v191 offset:18432
	ds_read_b128 v[186:189], v191 offset:19456
	ds_read_b128 v[192:195], v191 offset:20480
	ds_read_b128 v[196:199], v191 offset:21504
	ds_read_b128 v[200:203], v191 offset:22528
	ds_read_b128 v[204:207], v191 offset:23552
	global_load_lds_dwordx4 v128, s[46:47]
	s_add_i32 m0, s8, 0x2000
	s_add_u32 s84, s46, 0xb0000
	s_addc_u32 s85, s47, 0
	s_add_i32 s8, s88, s14
	global_load_lds_dwordx4 v146, s[46:47]
	s_mov_b32 m0, s8
	s_nop 0
	global_load_lds_dwordx4 v128, s[84:85]
	s_add_i32 m0, s8, 0x2000
	s_nop 0
	global_load_lds_dwordx4 v146, s[84:85]
	s_mov_b32 m0, s15
	s_nop 0
	global_load_lds_dwordx4 v150, s[64:65]
	s_mov_b32 m0, s18
	s_nop 0
	global_load_lds_dwordx4 v148, s[64:65]
	s_add_u32 s100, s64, 0x80
	s_addc_u32 s101, s65, 0
	s_waitcnt vmcnt(8)
	s_waitcnt lgkmcnt(0)
	s_barrier
	s_setprio 1
	s_waitcnt lgkmcnt(0)
	v_mfma_f32_16x16x32_bf16 v[60:63], v[130:133], v[172:175], v[60:63]
	v_mfma_f32_16x16x32_bf16 v[56:59], v[138:141], v[172:175], v[56:59]
	v_mfma_f32_16x16x32_bf16 v[44:47], v[130:133], v[180:183], v[44:47]
	v_mfma_f32_16x16x32_bf16 v[40:43], v[138:141], v[180:183], v[40:43]
	v_mfma_f32_16x16x32_bf16 v[28:31], v[130:133], v[192:195], v[28:31]
	v_mfma_f32_16x16x32_bf16 v[24:27], v[138:141], v[192:195], v[24:27]
	v_mfma_f32_16x16x32_bf16 v[12:15], v[130:133], v[200:203], v[12:15]
	v_mfma_f32_16x16x32_bf16 v[8:11], v[138:141], v[200:203], v[8:11]
	v_mfma_f32_16x16x32_bf16 v[60:63], v[134:137], v[176:179], v[60:63]
	v_mfma_f32_16x16x32_bf16 v[56:59], v[142:145], v[176:179], v[56:59]
	v_mfma_f32_16x16x32_bf16 v[44:47], v[134:137], v[186:189], v[44:47]
	v_mfma_f32_16x16x32_bf16 v[40:43], v[142:145], v[186:189], v[40:43]
	v_mfma_f32_16x16x32_bf16 v[28:31], v[134:137], v[196:199], v[28:31]
	v_mfma_f32_16x16x32_bf16 v[24:27], v[142:145], v[196:199], v[24:27]
	v_mfma_f32_16x16x32_bf16 v[12:15], v[134:137], v[204:207], v[12:15]
	v_mfma_f32_16x16x32_bf16 v[8:11], v[142:145], v[204:207], v[8:11]
	s_setprio 0
	s_setprio 1
	v_mfma_f32_16x16x32_bf16 v[52:55], v[156:159], v[172:175], v[52:55]
	v_mfma_f32_16x16x32_bf16 v[48:51], v[164:167], v[172:175], v[48:51]
	v_mfma_f32_16x16x32_bf16 v[36:39], v[156:159], v[180:183], v[36:39]
	v_mfma_f32_16x16x32_bf16 v[32:35], v[164:167], v[180:183], v[32:35]
	v_mfma_f32_16x16x32_bf16 v[20:23], v[156:159], v[192:195], v[20:23]
	v_mfma_f32_16x16x32_bf16 v[16:19], v[164:167], v[192:195], v[16:19]
	v_mfma_f32_16x16x32_bf16 v[4:7], v[156:159], v[200:203], v[4:7]
	v_mfma_f32_16x16x32_bf16 v[0:3], v[164:167], v[200:203], v[0:3]
	v_mfma_f32_16x16x32_bf16 v[52:55], v[160:163], v[176:179], v[52:55]
	v_mfma_f32_16x16x32_bf16 v[48:51], v[168:171], v[176:179], v[48:51]
	v_mfma_f32_16x16x32_bf16 v[36:39], v[160:163], v[186:189], v[36:39]
	v_mfma_f32_16x16x32_bf16 v[32:35], v[168:171], v[186:189], v[32:35]
	v_mfma_f32_16x16x32_bf16 v[20:23], v[160:163], v[196:199], v[20:23]
	v_mfma_f32_16x16x32_bf16 v[16:19], v[168:171], v[196:199], v[16:19]
	v_mfma_f32_16x16x32_bf16 v[4:7], v[160:163], v[204:207], v[4:7]
	v_mfma_f32_16x16x32_bf16 v[0:3], v[168:171], v[204:207], v[0:3]
	s_setprio 0
	s_barrier
; #define PG8_STAGE(bufoff, gbase, voff) do { _Pragma("unroll") for (int _i = 0; _i < 2; ++_i) \
;         __builtin_amdgcn_global_load_lds((const unsigned*)((const char*)(gbase) + (voff)[_i]), (PG8_LAS unsigned*)(lds + (bufoff) + ldsw + _i * 8192), 16, 0, 0); } while (0)
; #define PG8_LDA(dst, b, h) do { _Pragma("unroll") for (int m = 0; m < 4; ++m) _Pragma("unroll") for (int k = 0; k < 2; ++k) dst[m][k] = *(const PG8_LAS bf16x8*)(lds + PG8_SA(b, h) + aoff + m * 2048 + k * 1024); } while (0)
; #define PG8_LDB(dst, b, h) do { _Pragma("unroll") for (int n = 0; n < 2; ++n) _Pragma("unroll") for (int k = 0; k < 2; ++k) dst[n][k] = *(const PG8_LAS bf16x8*)(lds + PG8_SB(b, h) + boff + n * 2048 + k * 1024); } while (0)
; #define PG8_MMA(ai, bj, At, Bt) do { __builtin_amdgcn_s_setprio(1); _Pragma("unroll") for (int m = 0; m < 4; ++m) _Pragma("unroll") for (int n = 0; n < 2; ++n) _Pragma("unroll") for (int k = 0; k < 2; ++k) \
;         acc[ai][bj][m][n] = __builtin_amdgcn_mfma_f32_16x16x32_bf16(Bt[n][k], At[m][k], acc[ai][bj][m][n], 0, 0, 0); __builtin_amdgcn_s_setprio(0); } while (0)
; #define PG8_WAIT_V(n) asm volatile("s_waitcnt vmcnt(" #n ")" ::: "memory")
; #define PG8_WAIT_L(n) asm volatile("s_waitcnt lgkmcnt(" #n ")" ::: "memory")
; #define PG8_BAR __builtin_amdgcn_s_barrier()
; #define PG8_SCHED __builtin_amdgcn_sched_barrier(0)
; template <class Epi, class Sched, bool ALIGN_EPI = false, bool SP2 = false>
; __device__ __forceinline__ void gemm_phase(PG8_LAS unsigned char* lds, const Gemm g, const Sched& S, const Epi& E) {
;     ...
;             PG8_LDB(B0, 1, 0); PG8_LDB(B1, 1, 1); PG8_SCHED; PG8_LDA(At, 1, 0); PG8_STAGE(PG8_SA(0, 1), a2 + hstep, voffA);
;             PG8_WAIT_V(8); PG8_WAIT_L(0); PG8_BAR; PG8_MMA(0, 0, At, B0); PG8_MMA(0, 1, At, B1); PG8_BAR; PG8_SCHED;
;             PG8_LDA(At, 1, 1); PG8_STAGE(PG8_SB(1, 0), b3, voffB); PG8_STAGE(PG8_SB(1, 1), b3 + hstep, voffB); PG8_STAGE(PG8_SA(1, 0), a3, voffA);
;             PG8_WAIT_V(8); PG8_WAIT_L(0); PG8_BAR; PG8_MMA(1, 0, At, B0); PG8_MMA(1, 1, At, B1); PG8_BAR; PG8_SCHED;
	s_add_i32 s8, 0, 0x18000
	s_add_i32 s84, 0, 0x1c000
	v_add_u32_e32 v142, s8, v185
	v_add_u32_e32 v168, s84, v185
	ds_read_b128 v[130:133], v142
	ds_read_b128 v[134:137], v142 offset:1024
	ds_read_b128 v[138:141], v142 offset:2048
	ds_read_b128 v[142:145], v142 offset:3072
	ds_read_b128 v[156:159], v168
	ds_read_b128 v[160:163], v168 offset:1024
	ds_read_b128 v[164:167], v168 offset:2048
	ds_read_b128 v[168:171], v168 offset:3072
	s_add_u32 s64, s64, 0xb0000
	s_addc_u32 s65, s65, 0
	s_mov_b32 m0, s19
	ds_read_b128 v[172:175], v191 offset:32768
	ds_read_b128 v[176:179], v191 offset:33792
	ds_read_b128 v[180:183], v191 offset:34816
	ds_read_b128 v[186:189], v191 offset:35840
	ds_read_b128 v[192:195], v191 offset:36864
	ds_read_b128 v[196:199], v191 offset:37888
	ds_read_b128 v[200:203], v191 offset:38912
	ds_read_b128 v[204:207], v191 offset:39936
	global_load_lds_dwordx4 v150, s[64:65]
	s_mov_b32 m0, s20
	s_nop 0
	global_load_lds_dwordx4 v148, s[64:65]
	s_waitcnt vmcnt(8)
	s_waitcnt lgkmcnt(0)
	s_barrier
	s_setprio 1
	s_waitcnt lgkmcnt(0)
	v_mfma_f32_16x16x32_bf16 v[124:127], v[130:133], v[172:175], v[124:127]
	v_mfma_f32_16x16x32_bf16 v[120:123], v[138:141], v[172:175], v[120:123]
	v_mfma_f32_16x16x32_bf16 v[108:111], v[130:133], v[180:183], v[108:111]
	v_mfma_f32_16x16x32_bf16 v[104:107], v[138:141], v[180:183], v[104:107]
	v_mfma_f32_16x16x32_bf16 v[92:95], v[130:133], v[192:195], v[92:95]
	v_mfma_f32_16x16x32_bf16 v[88:91], v[138:141], v[192:195], v[88:91]
	v_mfma_f32_16x16x32_bf16 v[76:79], v[130:133], v[200:203], v[76:79]
	v_mfma_f32_16x16x32_bf16 v[72:75], v[138:141], v[200:203], v[72:75]
	v_mfma_f32_16x16x32_bf16 v[124:127], v[134:137], v[176:179], v[124:127]
	v_mfma_f32_16x16x32_bf16 v[120:123], v[142:145], v[176:179], v[120:123]
	v_mfma_f32_16x16x32_bf16 v[108:111], v[134:137], v[186:189], v[108:111]
	v_mfma_f32_16x16x32_bf16 v[104:107], v[142:145], v[186:189], v[104:107]
	v_mfma_f32_16x16x32_bf16 v[92:95], v[134:137], v[196:199], v[92:95]
	v_mfma_f32_16x16x32_bf16 v[88:91], v[142:145], v[196:199], v[88:91]
	v_mfma_f32_16x16x32_bf16 v[76:79], v[134:137], v[204:207], v[76:79]
	v_mfma_f32_16x16x32_bf16 v[72:75], v[142:145], v[204:207], v[72:75]
	s_setprio 0
	s_setprio 1
	v_mfma_f32_16x16x32_bf16 v[116:119], v[156:159], v[172:175], v[116:119]
	v_mfma_f32_16x16x32_bf16 v[112:115], v[164:167], v[172:175], v[112:115]
	v_mfma_f32_16x16x32_bf16 v[100:103], v[156:159], v[180:183], v[100:103]
	v_mfma_f32_16x16x32_bf16 v[96:99], v[164:167], v[180:183], v[96:99]
	v_mfma_f32_16x16x32_bf16 v[84:87], v[156:159], v[192:195], v[84:87]
	v_mfma_f32_16x16x32_bf16 v[80:83], v[164:167], v[192:195], v[80:83]
	v_mfma_f32_16x16x32_bf16 v[68:71], v[156:159], v[200:203], v[68:71]
	v_mfma_f32_16x16x32_bf16 v[64:67], v[164:167], v[200:203], v[64:67]
	v_mfma_f32_16x16x32_bf16 v[116:119], v[160:163], v[176:179], v[116:119]
	v_mfma_f32_16x16x32_bf16 v[112:115], v[168:171], v[176:179], v[112:115]
	v_mfma_f32_16x16x32_bf16 v[100:103], v[160:163], v[186:189], v[100:103]
	v_mfma_f32_16x16x32_bf16 v[96:99], v[168:171], v[186:189], v[96:99]
	v_mfma_f32_16x16x32_bf16 v[84:87], v[160:163], v[196:199], v[84:87]
	v_mfma_f32_16x16x32_bf16 v[80:83], v[168:171], v[196:199], v[80:83]
	v_mfma_f32_16x16x32_bf16 v[68:71], v[160:163], v[204:207], v[68:71]
	v_mfma_f32_16x16x32_bf16 v[64:67], v[168:171], v[204:207], v[64:67]
	s_setprio 0
	s_barrier
	s_add_i32 s8, s8, s14
	s_add_i32 m0, s8, 0xffffff80
	ds_read_b128 v[172:175], v191 offset:49152
	ds_read_b128 v[176:179], v191 offset:50176
	ds_read_b128 v[180:183], v191 offset:51200
	ds_read_b128 v[186:189], v191 offset:52224
	ds_read_b128 v[192:195], v191 offset:53248
	ds_read_b128 v[196:199], v191 offset:54272
	ds_read_b128 v[200:203], v191 offset:55296
	ds_read_b128 v[204:207], v191 offset:56320
	global_load_lds_dwordx4 v128, s[46:47] offset:128
	s_add_i32 m0, s8, 0x1f80
	s_add_i32 s8, s84, s14
	global_load_lds_dwordx4 v146, s[46:47] offset:128
	s_add_u32 s46, s46, 0xb0080
	s_addc_u32 s47, s47, 0
	s_mov_b32 m0, s8
	s_nop 0
	global_load_lds_dwordx4 v128, s[46:47]
	s_add_i32 m0, s8, 0x2000
	s_nop 0
	global_load_lds_dwordx4 v146, s[46:47]
	s_mov_b32 m0, s27
	s_nop 0
	global_load_lds_dwordx4 v150, s[100:101]
	s_mov_b32 m0, s28
	s_nop 0
	global_load_lds_dwordx4 v148, s[100:101]
	s_waitcnt vmcnt(8)
	s_waitcnt lgkmcnt(0)
	s_barrier
	s_setprio 1
	s_waitcnt lgkmcnt(0)
	v_mfma_f32_16x16x32_bf16 v[60:63], v[130:133], v[172:175], v[60:63]
	v_mfma_f32_16x16x32_bf16 v[56:59], v[138:141], v[172:175], v[56:59]
	v_mfma_f32_16x16x32_bf16 v[44:47], v[130:133], v[180:183], v[44:47]
	v_mfma_f32_16x16x32_bf16 v[40:43], v[138:141], v[180:183], v[40:43]
	v_mfma_f32_16x16x32_bf16 v[28:31], v[130:133], v[192:195], v[28:31]
	v_mfma_f32_16x16x32_bf16 v[24:27], v[138:141], v[192:195], v[24:27]
	v_mfma_f32_16x16x32_bf16 v[12:15], v[130:133], v[200:203], v[12:15]
	v_mfma_f32_16x16x32_bf16 v[8:11], v[138:141], v[200:203], v[8:11]
	v_mfma_f32_16x16x32_bf16 v[60:63], v[134:137], v[176:179], v[60:63]
	v_mfma_f32_16x16x32_bf16 v[56:59], v[142:145], v[176:179], v[56:59]
	v_mfma_f32_16x16x32_bf16 v[44:47], v[134:137], v[186:189], v[44:47]
	v_mfma_f32_16x16x32_bf16 v[40:43], v[142:145], v[186:189], v[40:43]
	v_mfma_f32_16x16x32_bf16 v[28:31], v[134:137], v[196:199], v[28:31]
	v_mfma_f32_16x16x32_bf16 v[24:27], v[142:145], v[196:199], v[24:27]
	v_mfma_f32_16x16x32_bf16 v[12:15], v[134:137], v[204:207], v[12:15]
	v_mfma_f32_16x16x32_bf16 v[8:11], v[142:145], v[204:207], v[8:11]
	s_setprio 0
	s_setprio 1
	v_mfma_f32_16x16x32_bf16 v[52:55], v[156:159], v[172:175], v[52:55]
	v_mfma_f32_16x16x32_bf16 v[48:51], v[164:167], v[172:175], v[48:51]
	v_mfma_f32_16x16x32_bf16 v[36:39], v[156:159], v[180:183], v[36:39]
	v_mfma_f32_16x16x32_bf16 v[32:35], v[164:167], v[180:183], v[32:35]
	v_mfma_f32_16x16x32_bf16 v[20:23], v[156:159], v[192:195], v[20:23]
	v_mfma_f32_16x16x32_bf16 v[16:19], v[164:167], v[192:195], v[16:19]
	v_mfma_f32_16x16x32_bf16 v[4:7], v[156:159], v[200:203], v[4:7]
	v_mfma_f32_16x16x32_bf16 v[0:3], v[164:167], v[200:203], v[0:3]
	v_mfma_f32_16x16x32_bf16 v[52:55], v[160:163], v[176:179], v[52:55]
	v_mfma_f32_16x16x32_bf16 v[48:51], v[168:171], v[176:179], v[48:51]
	v_mfma_f32_16x16x32_bf16 v[36:39], v[160:163], v[186:189], v[36:39]
	v_mfma_f32_16x16x32_bf16 v[32:35], v[168:171], v[186:189], v[32:35]
	v_mfma_f32_16x16x32_bf16 v[20:23], v[160:163], v[196:199], v[20:23]
	v_mfma_f32_16x16x32_bf16 v[16:19], v[168:171], v[196:199], v[16:19]
	v_mfma_f32_16x16x32_bf16 v[4:7], v[160:163], v[204:207], v[4:7]
	v_mfma_f32_16x16x32_bf16 v[0:3], v[168:171], v[204:207], v[0:3]
	s_setprio 0
	s_barrier
	s_add_i32 s70, s70, 2
	s_add_u32 s36, s36, 0x100
	s_addc_u32 s37, s37, 0
	s_cmp_gt_u32 s70, 41
	s_mov_b64 s[96:97], s[44:45]
	s_cbranch_scc0 .LBB0_957
	s_and_b64 vcc, exec, s[58:59]
	s_cbranch_vccz .LBB0_960
	s_barrier

; #define PG8_STAGE(bufoff, gbase, voff) do { _Pragma("unroll") for (int _i = 0; _i < 2; ++_i) \
;         __builtin_amdgcn_global_load_lds((const unsigned*)((const char*)(gbase) + (voff)[_i]), (PG8_LAS unsigned*)(lds + (bufoff) + ldsw + _i * 8192), 16, 0, 0); } while (0)
; #define PG8_LDA(dst, b, h) do { _Pragma("unroll") for (int m = 0; m < 4; ++m) _Pragma("unroll") for (int k = 0; k < 2; ++k) dst[m][k] = *(const PG8_LAS bf16x8*)(lds + PG8_SA(b, h) + aoff + m * 2048 + k * 1024); } while (0)
; #define PG8_LDB(dst, b, h) do { _Pragma("unroll") for (int n = 0; n < 2; ++n) _Pragma("unroll") for (int k = 0; k < 2; ++k) dst[n][k] = *(const PG8_LAS bf16x8*)(lds + PG8_SB(b, h) + boff + n * 2048 + k * 1024); } while (0)
; #define PG8_MMA(ai, bj, At, Bt) do { __builtin_amdgcn_s_setprio(1); _Pragma("unroll") for (int m = 0; m < 4; ++m) _Pragma("unroll") for (int n = 0; n < 2; ++n) _Pragma("unroll") for (int k = 0; k < 2; ++k) \
;         acc[ai][bj][m][n] = __builtin_amdgcn_mfma_f32_16x16x32_bf16(Bt[n][k], At[m][k], acc[ai][bj][m][n], 0, 0, 0); __builtin_amdgcn_s_setprio(0); } while (0)
; #define PG8_WAIT_V(n) asm volatile("s_waitcnt vmcnt(" #n ")" ::: "memory")
; #define PG8_BAR __builtin_amdgcn_s_barrier()
; template <class Epi, class Sched, bool ALIGN_EPI = false, bool SP2 = false>
; __device__ __forceinline__ void gemm_phase(PG8_LAS unsigned char* lds, const Gemm g, const Sched& S, const Epi& E) {
;     ...
;         for (int t = 0; t < nt; t += 2) {
;             const bool last = (t == nt - 2);
;             const char* a1 = cA + (size_t)(t + 1) * kstep;
;             const char* a2 = last ? nA : cA + (size_t)(t + 2) * kstep; const char* b2 = last ? nB : cB + (size_t)(t + 2) * kstep;
;             const char* a3 = a2 + kstep; const char* b3 = b2 + kstep;
;             if (last && has_next) S.a_ready(nxt);
;             if constexpr (SP2) {
;             PG8_LDB(B0, 0, 0); PG8_LDB(B1, 0, 1); PG8_SCHED; PG8_LDA(At, 0, 0); PG8_STAGE(PG8_SA(1, 1), a1 + hstep, voffA);
;             PG8_WAIT_V(8); PG8_WAIT_L(0); PG8_BAR; PG8_MMA(0, 0, At, B0); PG8_MMA(0, 1, At, B1); PG8_BAR; PG8_SCHED;
;             PG8_LDA(At, 0, 1); PG8_STAGE(PG8_SB(0, 0), b2, voffB); PG8_STAGE(PG8_SB(0, 1), b2 + hstep, voffB); PG8_STAGE(PG8_SA(0, 0), a2, voffA);
;             PG8_WAIT_V(8); PG8_WAIT_L(0); PG8_BAR; PG8_MMA(1, 0, At, B0); PG8_MMA(1, 1, At, B1); PG8_BAR; PG8_SCHED;
.LBB0_995:
	s_add_u32 s42, s96, 0x100
	s_addc_u32 s43, s97, 0
	s_add_i32 s8, 0, 0x10000
	s_cmp_eq_u32 s84, 40
	s_cselect_b32 s65, s67, s43
	s_cselect_b32 s64, s66, s42
	s_cselect_b32 s47, s73, s37
	s_cselect_b32 s46, s72, s36
	s_add_i32 s85, 0, 0x14000
	v_add_u32_e32 v142, s8, v201
	v_add_u32_e32 v168, s85, v201
	ds_read_b128 v[130:133], v142
	ds_read_b128 v[134:137], v142 offset:1024
	ds_read_b128 v[138:141], v142 offset:2048
	ds_read_b128 v[142:145], v142 offset:3072
	ds_read_b128 v[156:159], v168
	ds_read_b128 v[160:163], v168 offset:1024
	ds_read_b128 v[164:167], v168 offset:2048
	ds_read_b128 v[168:171], v168 offset:3072
	s_add_i32 m0, s15, 0xc000
	ds_read_b128 v[172:175], v203
	ds_read_b128 v[176:179], v203 offset:1024
	ds_read_b128 v[180:183], v203 offset:2048
	ds_read_b128 v[184:187], v203 offset:3072
	ds_read_b128 v[188:191], v203 offset:4096
	ds_read_b128 v[192:195], v203 offset:5120
	ds_read_b128 v[196:199], v203 offset:6144
	ds_read_b128 v[204:207], v203 offset:7168
	global_load_lds_dwordx4 v152, s[96:97]
	s_add_i32 m0, s15, 0xe000
	s_nop 0
	global_load_lds_dwordx4 v154, s[96:97]
	s_waitcnt vmcnt(8)
	s_waitcnt lgkmcnt(0)
	s_barrier
	s_setprio 1
	s_waitcnt lgkmcnt(0)
	v_mfma_f32_16x16x32_bf16 v[124:127], v[130:133], v[172:175], v[124:127]
	v_mfma_f32_16x16x32_bf16 v[120:123], v[138:141], v[172:175], v[120:123]
	v_mfma_f32_16x16x32_bf16 v[108:111], v[130:133], v[180:183], v[108:111]
	v_mfma_f32_16x16x32_bf16 v[104:107], v[138:141], v[180:183], v[104:107]
	v_mfma_f32_16x16x32_bf16 v[92:95], v[130:133], v[188:191], v[92:95]
	v_mfma_f32_16x16x32_bf16 v[88:91], v[138:141], v[188:191], v[88:91]
	v_mfma_f32_16x16x32_bf16 v[76:79], v[130:133], v[196:199], v[76:79]
	v_mfma_f32_16x16x32_bf16 v[72:75], v[138:141], v[196:199], v[72:75]
	v_mfma_f32_16x16x32_bf16 v[124:127], v[134:137], v[176:179], v[124:127]
	v_mfma_f32_16x16x32_bf16 v[120:123], v[142:145], v[176:179], v[120:123]
	v_mfma_f32_16x16x32_bf16 v[108:111], v[134:137], v[184:187], v[108:111]
	v_mfma_f32_16x16x32_bf16 v[104:107], v[142:145], v[184:187], v[104:107]
	v_mfma_f32_16x16x32_bf16 v[92:95], v[134:137], v[192:195], v[92:95]
	v_mfma_f32_16x16x32_bf16 v[88:91], v[142:145], v[192:195], v[88:91]
	v_mfma_f32_16x16x32_bf16 v[76:79], v[134:137], v[204:207], v[76:79]
	v_mfma_f32_16x16x32_bf16 v[72:75], v[142:145], v[204:207], v[72:75]
	s_setprio 0
	s_setprio 1
	v_mfma_f32_16x16x32_bf16 v[116:119], v[156:159], v[172:175], v[116:119]
	v_mfma_f32_16x16x32_bf16 v[112:115], v[164:167], v[172:175], v[112:115]
	v_mfma_f32_16x16x32_bf16 v[100:103], v[156:159], v[180:183], v[100:103]
	v_mfma_f32_16x16x32_bf16 v[96:99], v[164:167], v[180:183], v[96:99]
	v_mfma_f32_16x16x32_bf16 v[84:87], v[156:159], v[188:191], v[84:87]
	v_mfma_f32_16x16x32_bf16 v[80:83], v[164:167], v[188:191], v[80:83]
	v_mfma_f32_16x16x32_bf16 v[68:71], v[156:159], v[196:199], v[68:71]
	v_mfma_f32_16x16x32_bf16 v[64:67], v[164:167], v[196:199], v[64:67]
	v_mfma_f32_16x16x32_bf16 v[116:119], v[160:163], v[176:179], v[116:119]
	v_mfma_f32_16x16x32_bf16 v[112:115], v[168:171], v[176:179], v[112:115]
	v_mfma_f32_16x16x32_bf16 v[100:103], v[160:163], v[184:187], v[100:103]
	v_mfma_f32_16x16x32_bf16 v[96:99], v[168:171], v[184:187], v[96:99]
	v_mfma_f32_16x16x32_bf16 v[84:87], v[160:163], v[192:195], v[84:87]
	v_mfma_f32_16x16x32_bf16 v[80:83], v[168:171], v[192:195], v[80:83]
	v_mfma_f32_16x16x32_bf16 v[68:71], v[160:163], v[204:207], v[68:71]
	v_mfma_f32_16x16x32_bf16 v[64:67], v[168:171], v[204:207], v[64:67]
	s_setprio 0
	s_barrier
	s_add_i32 s8, s8, s14
	s_mov_b32 m0, s8
	ds_read_b128 v[172:175], v203 offset:16384
	ds_read_b128 v[176:179], v203 offset:17408
	ds_read_b128 v[180:183], v203 offset:18432
	ds_read_b128 v[184:187], v203 offset:19456
	ds_read_b128 v[188:191], v203 offset:20480
	ds_read_b128 v[192:195], v203 offset:21504
	ds_read_b128 v[196:199], v203 offset:22528
	ds_read_b128 v[204:207], v203 offset:23552
	global_load_lds_dwordx4 v128, s[46:47]
	s_add_i32 m0, s8, 0x2000
	s_add_u32 s96, s46, 0xb0000
	s_addc_u32 s97, s47, 0
	s_add_i32 s8, s85, s14
	global_load_lds_dwordx4 v146, s[46:47]
	s_mov_b32 m0, s8
	s_nop 0
	global_load_lds_dwordx4 v128, s[96:97]
	s_add_i32 m0, s8, 0x2000
	s_nop 0
	global_load_lds_dwordx4 v146, s[96:97]
	s_mov_b32 m0, s15
	s_nop 0
	global_load_lds_dwordx4 v150, s[64:65]
	s_mov_b32 m0, s18
	s_nop 0
	global_load_lds_dwordx4 v148, s[64:65]
	s_add_u32 s100, s64, 0x80
	s_addc_u32 s101, s65, 0
	s_waitcnt vmcnt(8)
	s_waitcnt lgkmcnt(0)
	s_barrier
	s_setprio 1
	s_waitcnt lgkmcnt(0)
	v_mfma_f32_16x16x32_bf16 v[60:63], v[130:133], v[172:175], v[60:63]
	v_mfma_f32_16x16x32_bf16 v[56:59], v[138:141], v[172:175], v[56:59]
	v_mfma_f32_16x16x32_bf16 v[44:47], v[130:133], v[180:183], v[44:47]
	v_mfma_f32_16x16x32_bf16 v[40:43], v[138:141], v[180:183], v[40:43]
	v_mfma_f32_16x16x32_bf16 v[28:31], v[130:133], v[188:191], v[28:31]
	v_mfma_f32_16x16x32_bf16 v[24:27], v[138:141], v[188:191], v[24:27]
	v_mfma_f32_16x16x32_bf16 v[12:15], v[130:133], v[196:199], v[12:15]
	v_mfma_f32_16x16x32_bf16 v[8:11], v[138:141], v[196:199], v[8:11]
	v_mfma_f32_16x16x32_bf16 v[60:63], v[134:137], v[176:179], v[60:63]
	v_mfma_f32_16x16x32_bf16 v[56:59], v[142:145], v[176:179], v[56:59]
	v_mfma_f32_16x16x32_bf16 v[44:47], v[134:137], v[184:187], v[44:47]
	v_mfma_f32_16x16x32_bf16 v[40:43], v[142:145], v[184:187], v[40:43]
	v_mfma_f32_16x16x32_bf16 v[28:31], v[134:137], v[192:195], v[28:31]
	v_mfma_f32_16x16x32_bf16 v[24:27], v[142:145], v[192:195], v[24:27]
	v_mfma_f32_16x16x32_bf16 v[12:15], v[134:137], v[204:207], v[12:15]
	v_mfma_f32_16x16x32_bf16 v[8:11], v[142:145], v[204:207], v[8:11]
	s_setprio 0
	s_setprio 1
	v_mfma_f32_16x16x32_bf16 v[52:55], v[156:159], v[172:175], v[52:55]
	v_mfma_f32_16x16x32_bf16 v[48:51], v[164:167], v[172:175], v[48:51]
	v_mfma_f32_16x16x32_bf16 v[36:39], v[156:159], v[180:183], v[36:39]
	v_mfma_f32_16x16x32_bf16 v[32:35], v[164:167], v[180:183], v[32:35]
	v_mfma_f32_16x16x32_bf16 v[20:23], v[156:159], v[188:191], v[20:23]
	v_mfma_f32_16x16x32_bf16 v[16:19], v[164:167], v[188:191], v[16:19]
	v_mfma_f32_16x16x32_bf16 v[4:7], v[156:159], v[196:199], v[4:7]
	v_mfma_f32_16x16x32_bf16 v[0:3], v[164:167], v[196:199], v[0:3]
	v_mfma_f32_16x16x32_bf16 v[52:55], v[160:163], v[176:179], v[52:55]
	v_mfma_f32_16x16x32_bf16 v[48:51], v[168:171], v[176:179], v[48:51]
	v_mfma_f32_16x16x32_bf16 v[36:39], v[160:163], v[184:187], v[36:39]
	v_mfma_f32_16x16x32_bf16 v[32:35], v[168:171], v[184:187], v[32:35]
	v_mfma_f32_16x16x32_bf16 v[20:23], v[160:163], v[192:195], v[20:23]
	v_mfma_f32_16x16x32_bf16 v[16:19], v[168:171], v[192:195], v[16:19]
	v_mfma_f32_16x16x32_bf16 v[4:7], v[160:163], v[204:207], v[4:7]
	v_mfma_f32_16x16x32_bf16 v[0:3], v[168:171], v[204:207], v[0:3]
	s_setprio 0
	s_barrier
; #define PG8_STAGE(bufoff, gbase, voff) do { _Pragma("unroll") for (int _i = 0; _i < 2; ++_i) \
;         __builtin_amdgcn_global_load_lds((const unsigned*)((const char*)(gbase) + (voff)[_i]), (PG8_LAS unsigned*)(lds + (bufoff) + ldsw + _i * 8192), 16, 0, 0); } while (0)
; #define PG8_LDA(dst, b, h) do { _Pragma("unroll") for (int m = 0; m < 4; ++m) _Pragma("unroll") for (int k = 0; k < 2; ++k) dst[m][k] = *(const PG8_LAS bf16x8*)(lds + PG8_SA(b, h) + aoff + m * 2048 + k * 1024); } while (0)
; #define PG8_LDB(dst, b, h) do { _Pragma("unroll") for (int n = 0; n < 2; ++n) _Pragma("unroll") for (int k = 0; k < 2; ++k) dst[n][k] = *(const PG8_LAS bf16x8*)(lds + PG8_SB(b, h) + boff + n * 2048 + k * 1024); } while (0)
; #define PG8_MMA(ai, bj, At, Bt) do { __builtin_amdgcn_s_setprio(1); _Pragma("unroll") for (int m = 0; m < 4; ++m) _Pragma("unroll") for (int n = 0; n < 2; ++n) _Pragma("unroll") for (int k = 0; k < 2; ++k) \
;         acc[ai][bj][m][n] = __builtin_amdgcn_mfma_f32_16x16x32_bf16(Bt[n][k], At[m][k], acc[ai][bj][m][n], 0, 0, 0); __builtin_amdgcn_s_setprio(0); } while (0)
; #define PG8_WAIT_V(n) asm volatile("s_waitcnt vmcnt(" #n ")" ::: "memory")
; #define PG8_WAIT_L(n) asm volatile("s_waitcnt lgkmcnt(" #n ")" ::: "memory")
; #define PG8_BAR __builtin_amdgcn_s_barrier()
; #define PG8_SCHED __builtin_amdgcn_sched_barrier(0)
; template <class Epi, class Sched, bool ALIGN_EPI = false, bool SP2 = false>
; __device__ __forceinline__ void gemm_phase(PG8_LAS unsigned char* lds, const Gemm g, const Sched& S, const Epi& E) {
;     ...
;             PG8_LDB(B0, 1, 0); PG8_LDB(B1, 1, 1); PG8_SCHED; PG8_LDA(At, 1, 0); PG8_STAGE(PG8_SA(0, 1), a2 + hstep, voffA);
;             PG8_WAIT_V(8); PG8_WAIT_L(0); PG8_BAR; PG8_MMA(0, 0, At, B0); PG8_MMA(0, 1, At, B1); PG8_BAR; PG8_SCHED;
;             PG8_LDA(At, 1, 1); PG8_STAGE(PG8_SB(1, 0), b3, voffB); PG8_STAGE(PG8_SB(1, 1), b3 + hstep, voffB); PG8_STAGE(PG8_SA(1, 0), a3, voffA);
;             PG8_WAIT_V(8); PG8_WAIT_L(0); PG8_BAR; PG8_MMA(1, 0, At, B0); PG8_MMA(1, 1, At, B1); PG8_BAR; PG8_SCHED;
	s_add_i32 s8, 0, 0x18000
	s_add_i32 s85, 0, 0x1c000
	v_add_u32_e32 v142, s8, v201
	v_add_u32_e32 v168, s85, v201
	ds_read_b128 v[130:133], v142
	ds_read_b128 v[134:137], v142 offset:1024
	ds_read_b128 v[138:141], v142 offset:2048
	ds_read_b128 v[142:145], v142 offset:3072
	ds_read_b128 v[156:159], v168
	ds_read_b128 v[160:163], v168 offset:1024
	ds_read_b128 v[164:167], v168 offset:2048
	ds_read_b128 v[168:171], v168 offset:3072
	s_add_u32 s64, s64, 0xb0000
	s_addc_u32 s65, s65, 0
	s_mov_b32 m0, s19
	ds_read_b128 v[172:175], v203 offset:32768
	ds_read_b128 v[176:179], v203 offset:33792
	ds_read_b128 v[180:183], v203 offset:34816
	ds_read_b128 v[184:187], v203 offset:35840
	ds_read_b128 v[188:191], v203 offset:36864
	ds_read_b128 v[192:195], v203 offset:37888
	ds_read_b128 v[196:199], v203 offset:38912
	ds_read_b128 v[204:207], v203 offset:39936
	global_load_lds_dwordx4 v150, s[64:65]
	s_mov_b32 m0, s20
	s_nop 0
	global_load_lds_dwordx4 v148, s[64:65]
	s_waitcnt vmcnt(8)
	s_waitcnt lgkmcnt(0)
	s_barrier
	s_setprio 1
	s_waitcnt lgkmcnt(0)
	v_mfma_f32_16x16x32_bf16 v[124:127], v[130:133], v[172:175], v[124:127]
	v_mfma_f32_16x16x32_bf16 v[120:123], v[138:141], v[172:175], v[120:123]
	v_mfma_f32_16x16x32_bf16 v[108:111], v[130:133], v[180:183], v[108:111]
	v_mfma_f32_16x16x32_bf16 v[104:107], v[138:141], v[180:183], v[104:107]
	v_mfma_f32_16x16x32_bf16 v[92:95], v[130:133], v[188:191], v[92:95]
	v_mfma_f32_16x16x32_bf16 v[88:91], v[138:141], v[188:191], v[88:91]
	v_mfma_f32_16x16x32_bf16 v[76:79], v[130:133], v[196:199], v[76:79]
	v_mfma_f32_16x16x32_bf16 v[72:75], v[138:141], v[196:199], v[72:75]
	v_mfma_f32_16x16x32_bf16 v[124:127], v[134:137], v[176:179], v[124:127]
	v_mfma_f32_16x16x32_bf16 v[120:123], v[142:145], v[176:179], v[120:123]
	v_mfma_f32_16x16x32_bf16 v[108:111], v[134:137], v[184:187], v[108:111]
	v_mfma_f32_16x16x32_bf16 v[104:107], v[142:145], v[184:187], v[104:107]
	v_mfma_f32_16x16x32_bf16 v[92:95], v[134:137], v[192:195], v[92:95]
	v_mfma_f32_16x16x32_bf16 v[88:91], v[142:145], v[192:195], v[88:91]
	v_mfma_f32_16x16x32_bf16 v[76:79], v[134:137], v[204:207], v[76:79]
	v_mfma_f32_16x16x32_bf16 v[72:75], v[142:145], v[204:207], v[72:75]
	s_setprio 0
	s_setprio 1
	v_mfma_f32_16x16x32_bf16 v[116:119], v[156:159], v[172:175], v[116:119]
	v_mfma_f32_16x16x32_bf16 v[112:115], v[164:167], v[172:175], v[112:115]
	v_mfma_f32_16x16x32_bf16 v[100:103], v[156:159], v[180:183], v[100:103]
	v_mfma_f32_16x16x32_bf16 v[96:99], v[164:167], v[180:183], v[96:99]
	v_mfma_f32_16x16x32_bf16 v[84:87], v[156:159], v[188:191], v[84:87]
	v_mfma_f32_16x16x32_bf16 v[80:83], v[164:167], v[188:191], v[80:83]
	v_mfma_f32_16x16x32_bf16 v[68:71], v[156:159], v[196:199], v[68:71]
	v_mfma_f32_16x16x32_bf16 v[64:67], v[164:167], v[196:199], v[64:67]
	v_mfma_f32_16x16x32_bf16 v[116:119], v[160:163], v[176:179], v[116:119]
	v_mfma_f32_16x16x32_bf16 v[112:115], v[168:171], v[176:179], v[112:115]
	v_mfma_f32_16x16x32_bf16 v[100:103], v[160:163], v[184:187], v[100:103]
	v_mfma_f32_16x16x32_bf16 v[96:99], v[168:171], v[184:187], v[96:99]
	v_mfma_f32_16x16x32_bf16 v[84:87], v[160:163], v[192:195], v[84:87]
	v_mfma_f32_16x16x32_bf16 v[80:83], v[168:171], v[192:195], v[80:83]
	v_mfma_f32_16x16x32_bf16 v[68:71], v[160:163], v[204:207], v[68:71]
	v_mfma_f32_16x16x32_bf16 v[64:67], v[168:171], v[204:207], v[64:67]
	s_setprio 0
	s_barrier
	s_add_i32 s8, s8, s14
	s_add_i32 m0, s8, 0xffffff80
	ds_read_b128 v[172:175], v203 offset:49152
	ds_read_b128 v[176:179], v203 offset:50176
	ds_read_b128 v[180:183], v203 offset:51200
	ds_read_b128 v[184:187], v203 offset:52224
	ds_read_b128 v[188:191], v203 offset:53248
	ds_read_b128 v[192:195], v203 offset:54272
	ds_read_b128 v[196:199], v203 offset:55296
	ds_read_b128 v[204:207], v203 offset:56320
	global_load_lds_dwordx4 v128, s[46:47] offset:128
	s_add_i32 m0, s8, 0x1f80
	s_add_i32 s8, s85, s14
	global_load_lds_dwordx4 v146, s[46:47] offset:128
	s_add_u32 s46, s46, 0xb0080
	s_addc_u32 s47, s47, 0
	s_mov_b32 m0, s8
	s_nop 0
	global_load_lds_dwordx4 v128, s[46:47]
	s_add_i32 m0, s8, 0x2000
	s_nop 0
	global_load_lds_dwordx4 v146, s[46:47]
	s_mov_b32 m0, s29
	s_nop 0
	global_load_lds_dwordx4 v150, s[100:101]
	s_mov_b32 m0, s30
	s_nop 0
	global_load_lds_dwordx4 v148, s[100:101]
	s_waitcnt vmcnt(8)
	s_waitcnt lgkmcnt(0)
	s_barrier
	s_setprio 1
	s_waitcnt lgkmcnt(0)
	v_mfma_f32_16x16x32_bf16 v[60:63], v[130:133], v[172:175], v[60:63]
	v_mfma_f32_16x16x32_bf16 v[56:59], v[138:141], v[172:175], v[56:59]
	v_mfma_f32_16x16x32_bf16 v[44:47], v[130:133], v[180:183], v[44:47]
	v_mfma_f32_16x16x32_bf16 v[40:43], v[138:141], v[180:183], v[40:43]
	v_mfma_f32_16x16x32_bf16 v[28:31], v[130:133], v[188:191], v[28:31]
	v_mfma_f32_16x16x32_bf16 v[24:27], v[138:141], v[188:191], v[24:27]
	v_mfma_f32_16x16x32_bf16 v[12:15], v[130:133], v[196:199], v[12:15]
	v_mfma_f32_16x16x32_bf16 v[8:11], v[138:141], v[196:199], v[8:11]
	v_mfma_f32_16x16x32_bf16 v[60:63], v[134:137], v[176:179], v[60:63]
	v_mfma_f32_16x16x32_bf16 v[56:59], v[142:145], v[176:179], v[56:59]
	v_mfma_f32_16x16x32_bf16 v[44:47], v[134:137], v[184:187], v[44:47]
	v_mfma_f32_16x16x32_bf16 v[40:43], v[142:145], v[184:187], v[40:43]
	v_mfma_f32_16x16x32_bf16 v[28:31], v[134:137], v[192:195], v[28:31]
	v_mfma_f32_16x16x32_bf16 v[24:27], v[142:145], v[192:195], v[24:27]
	v_mfma_f32_16x16x32_bf16 v[12:15], v[134:137], v[204:207], v[12:15]
	v_mfma_f32_16x16x32_bf16 v[8:11], v[142:145], v[204:207], v[8:11]
	s_setprio 0
	s_setprio 1
	v_mfma_f32_16x16x32_bf16 v[52:55], v[156:159], v[172:175], v[52:55]
	v_mfma_f32_16x16x32_bf16 v[48:51], v[164:167], v[172:175], v[48:51]
	v_mfma_f32_16x16x32_bf16 v[36:39], v[156:159], v[180:183], v[36:39]
	v_mfma_f32_16x16x32_bf16 v[32:35], v[164:167], v[180:183], v[32:35]
	v_mfma_f32_16x16x32_bf16 v[20:23], v[156:159], v[188:191], v[20:23]
	v_mfma_f32_16x16x32_bf16 v[16:19], v[164:167], v[188:191], v[16:19]
	v_mfma_f32_16x16x32_bf16 v[4:7], v[156:159], v[196:199], v[4:7]
	v_mfma_f32_16x16x32_bf16 v[0:3], v[164:167], v[196:199], v[0:3]
	v_mfma_f32_16x16x32_bf16 v[52:55], v[160:163], v[176:179], v[52:55]
	v_mfma_f32_16x16x32_bf16 v[48:51], v[168:171], v[176:179], v[48:51]
	v_mfma_f32_16x16x32_bf16 v[36:39], v[160:163], v[184:187], v[36:39]
	v_mfma_f32_16x16x32_bf16 v[32:35], v[168:171], v[184:187], v[32:35]
	v_mfma_f32_16x16x32_bf16 v[20:23], v[160:163], v[192:195], v[20:23]
	v_mfma_f32_16x16x32_bf16 v[16:19], v[168:171], v[192:195], v[16:19]
	v_mfma_f32_16x16x32_bf16 v[4:7], v[160:163], v[204:207], v[4:7]
	v_mfma_f32_16x16x32_bf16 v[0:3], v[168:171], v[204:207], v[0:3]
	s_setprio 0
	s_barrier
	s_add_i32 s84, s84, 2
	s_add_u32 s36, s36, 0x100
	s_addc_u32 s37, s37, 0
	s_cmp_gt_u32 s84, 41
	s_mov_b64 s[96:97], s[42:43]
	s_cbranch_scc0 .LBB0_995
	s_and_b64 vcc, exec, s[62:63]
	s_cbranch_vccz .LBB0_998
	s_barrier

; __global__ void __launch_bounds__(NTHR, 2) mk_fwd(Args a) {
	.amdhsa_kernel _Z6mk_fwd4Args
		.amdhsa_group_segment_fixed_size 0
		.amdhsa_private_segment_fixed_size 0
		.amdhsa_kernarg_size 440
		.amdhsa_user_sgpr_count 2
		.amdhsa_user_sgpr_dispatch_ptr 0
		.amdhsa_user_sgpr_queue_ptr 0
		.amdhsa_user_sgpr_kernarg_segment_ptr 1
		.amdhsa_user_sgpr_dispatch_id 0
		.amdhsa_user_sgpr_kernarg_preload_length 0
		.amdhsa_user_sgpr_kernarg_preload_offset 0
		.amdhsa_user_sgpr_private_segment_size 0
		.amdhsa_uses_dynamic_stack 0
		.amdhsa_enable_private_segment 0
		.amdhsa_system_sgpr_workgroup_id_x 1
		.amdhsa_system_sgpr_workgroup_id_y 0
		.amdhsa_system_sgpr_workgroup_id_z 0
		.amdhsa_system_sgpr_workgroup_info 0
		.amdhsa_system_vgpr_workitem_id 2
		.amdhsa_next_free_vgpr 256
		.amdhsa_next_free_sgpr 102
		.amdhsa_accum_offset 256
		.amdhsa_reserve_vcc 1
		.amdhsa_float_round_mode_32 0
		.amdhsa_float_round_mode_16_64 0
		.amdhsa_float_denorm_mode_32 3
		.amdhsa_float_denorm_mode_16_64 3
		.amdhsa_dx10_clamp 1
		.amdhsa_ieee_mode 1
		.amdhsa_fp16_overflow 0
		.amdhsa_tg_split 0
		.amdhsa_exception_fp_ieee_invalid_op 0
		.amdhsa_exception_fp_denorm_src 0
		.amdhsa_exception_fp_ieee_div_zero 0
		.amdhsa_exception_fp_ieee_overflow 0
		.amdhsa_exception_fp_ieee_underflow 0
		.amdhsa_exception_fp_ieee_inexact 0
		.amdhsa_exception_int_div_zero 0
	.end_amdhsa_kernel

; __global__ void __launch_bounds__(NTHR, 2) mk_fwd(Args a) {
amdhsa.kernels:
  - .agpr_count:     0
    .args:
      - .offset:         0
        .size:           184
        .value_kind:     by_value
      - .offset:         184
        .size:           4
        .value_kind:     hidden_block_count_x
      - .offset:         188
        .size:           4
        .value_kind:     hidden_block_count_y
      - .offset:         192
        .size:           4
        .value_kind:     hidden_block_count_z
      - .offset:         196
        .size:           2
        .value_kind:     hidden_group_size_x
      - .offset:         198
        .size:           2
        .value_kind:     hidden_group_size_y
      - .offset:         200
        .size:           2
        .value_kind:     hidden_group_size_z
      - .offset:         202
        .size:           2
        .value_kind:     hidden_remainder_x
      - .offset:         204
        .size:           2
        .value_kind:     hidden_remainder_y
      - .offset:         206
        .size:           2
        .value_kind:     hidden_remainder_z
      - .offset:         224
        .size:           8
        .value_kind:     hidden_global_offset_x
      - .offset:         232
        .size:           8
        .value_kind:     hidden_global_offset_y
      - .offset:         240
        .size:           8
        .value_kind:     hidden_global_offset_z
      - .offset:         248
        .size:           2
        .value_kind:     hidden_grid_dims
      - .offset:         272
        .size:           8
        .value_kind:     hidden_multigrid_sync_arg
      - .offset:         304
        .size:           4
        .value_kind:     hidden_dynamic_lds_size
    .group_segment_fixed_size: 0
    .kernarg_segment_align: 8
    .kernarg_segment_size: 440
    .language:       OpenCL C
    .language_version:
      - 2
      - 0
    .max_flat_workgroup_size: 512
    .name:           _Z6mk_fwd4Args
    .private_segment_fixed_size: 0
    .sgpr_count:     108
    .sgpr_spill_count: 166
    .symbol:         _Z6mk_fwd4Args.kd
    .uniform_work_group_size: 1
    .uses_dynamic_stack: false
    .vgpr_count:     256
    .vgpr_spill_count: 0
    .wavefront_size: 64
